# first-tile q/k/v stores non-temporal on top of the second-tile write-through epilogue (quick timing already worse)
# baseline (speedup 1.0000x reference)
.Lq3_A:
	global_load_dwordx4 v[148:151], v133, s[24:25]
	global_load_dwordx4 v[152:155], v133, s[24:25] offset:16
	global_load_dwordx4 v[156:159], v133, s[24:25] offset:128
	global_load_dwordx4 v[160:163], v133, s[24:25] offset:144
	global_load_dwordx4 v[164:167], v131, s[8:9]
	global_load_dwordx4 v[168:171], v132, s[8:9]
	global_load_dwordx4 v[172:175], v131, s[8:9] offset:64
	global_load_dwordx4 v[176:179], v132, s[8:9] offset:64
	s_add_u32 s8, s8, 0x800
	s_addc_u32 s9, s9, 0
	global_load_dwordx4 v[202:205], v131, s[8:9]
	global_load_dwordx4 v[206:209], v132, s[8:9]
	global_load_dwordx4 v[210:213], v131, s[8:9] offset:64
	global_load_dwordx4 v[214:217], v132, s[8:9] offset:64
	v_mul_f32_e32 v134, v127, v127
	v_fmac_f32_e32 v134, v126, v126
	v_fmac_f32_e32 v134, v128, v128
	v_fmac_f32_e32 v134, v129, v129
	v_fmac_f32_e32 v134, v122, v122
	v_fmac_f32_e32 v134, v123, v123
	v_fmac_f32_e32 v134, v124, v124
	v_fmac_f32_e32 v134, v125, v125
	v_fmac_f32_e32 v134, v118, v118
	v_fmac_f32_e32 v134, v119, v119
	v_pk_mul_f32 v[136:137], v[120:121], v[120:121]
	v_pk_mul_f32 v[138:139], v[114:115], v[114:115]
	v_add_f32_e32 v134, v136, v134
	v_add_f32_e32 v134, v137, v134
	v_add_f32_e32 v134, v138, v134
	v_pk_mul_f32 v[136:137], v[116:117], v[116:117]
	v_add_f32_e32 v134, v139, v134
	v_add_f32_e32 v134, v136, v134
	v_add_f32_e32 v134, v137, v134
	ds_swizzle_b32 v135, v134 offset:swizzle(SWAP,16)
	s_waitcnt lgkmcnt(0)
	v_add_f32_e32 v134, v134, v135
	v_mov_b32_e32 v135, v134
	s_nop 1
	v_permlane32_swap_b32 v134, v135
	s_nop 1
	v_add_f32_e32 v134, v134, v135
	v_fmamk_f32 v134, v134, 0x3c800000, v242
	v_rsq_f32_e32 v134, v134
	s_waitcnt vmcnt(8)
	v_pk_mul_f32 v[136:137], v[134:135], v[148:149] op_sel_hi:[0,1]
	v_pk_mul_f32 v[126:127], v[126:127], v[136:137]
	v_pk_mul_f32 v[136:137], v[134:135], v[150:151] op_sel_hi:[0,1]
	v_pk_mul_f32 v[128:129], v[128:129], v[136:137]
	v_pk_mul_f32 v[136:137], v[134:135], v[152:153] op_sel_hi:[0,1]
	v_pk_mul_f32 v[122:123], v[122:123], v[136:137]
	v_pk_mul_f32 v[136:137], v[134:135], v[154:155] op_sel_hi:[0,1]
	v_pk_mul_f32 v[124:125], v[124:125], v[136:137]
	v_pk_mul_f32 v[136:137], v[134:135], v[156:157] op_sel_hi:[0,1]
	v_pk_mul_f32 v[118:119], v[118:119], v[136:137]
	v_pk_mul_f32 v[136:137], v[134:135], v[158:159] op_sel_hi:[0,1]
	v_pk_mul_f32 v[120:121], v[120:121], v[136:137]
	v_pk_mul_f32 v[136:137], v[134:135], v[160:161] op_sel_hi:[0,1]
	v_pk_mul_f32 v[114:115], v[114:115], v[136:137]
	v_pk_mul_f32 v[136:137], v[134:135], v[162:163] op_sel_hi:[0,1]
	v_pk_mul_f32 v[116:117], v[116:117], v[136:137]
	s_waitcnt vmcnt(4)
	v_pk_mul_f32 v[136:137], v[126:127], v[168:169] op_sel:[1,0] op_sel_hi:[0,0]
	v_pk_fma_f32 v[126:127], v[126:127], v[164:165], v[136:137] op_sel:[0,0,0] op_sel_hi:[1,0,1] neg_lo:[0,0,1]
	v_pk_mul_f32 v[136:137], v[128:129], v[168:169] op_sel:[1,1] op_sel_hi:[0,1]
	v_pk_fma_f32 v[128:129], v[128:129], v[164:165], v[136:137] op_sel:[0,1,0] op_sel_hi:[1,1,1] neg_lo:[0,0,1]
	v_pk_mul_f32 v[136:137], v[122:123], v[170:171] op_sel:[1,0] op_sel_hi:[0,0]
	v_pk_fma_f32 v[122:123], v[122:123], v[166:167], v[136:137] op_sel:[0,0,0] op_sel_hi:[1,0,1] neg_lo:[0,0,1]
	v_pk_mul_f32 v[136:137], v[124:125], v[170:171] op_sel:[1,1] op_sel_hi:[0,1]
	v_pk_fma_f32 v[124:125], v[124:125], v[166:167], v[136:137] op_sel:[0,1,0] op_sel_hi:[1,1,1] neg_lo:[0,0,1]
	v_pk_mul_f32 v[126:127], v[126:127], s[36:37] op_sel_hi:[1,0]
	v_pk_mul_f32 v[128:129], v[128:129], s[36:37] op_sel_hi:[1,0]
	v_pk_mul_f32 v[122:123], v[122:123], s[36:37] op_sel_hi:[1,0]
	v_pk_mul_f32 v[124:125], v[124:125], s[36:37] op_sel_hi:[1,0]
	v_cvt_pk_bf16_f32 v140, v126, v127
	v_cvt_pk_bf16_f32 v141, v128, v129
	v_cvt_pk_bf16_f32 v142, v122, v123
	v_cvt_pk_bf16_f32 v143, v124, v125
	v_pk_mul_f32 v[136:137], v[118:119], v[176:177] op_sel:[1,0] op_sel_hi:[0,0]
	v_pk_fma_f32 v[118:119], v[118:119], v[172:173], v[136:137] op_sel:[0,0,0] op_sel_hi:[1,0,1] neg_lo:[0,0,1]
	v_pk_mul_f32 v[136:137], v[120:121], v[176:177] op_sel:[1,1] op_sel_hi:[0,1]
	v_pk_fma_f32 v[120:121], v[120:121], v[172:173], v[136:137] op_sel:[0,1,0] op_sel_hi:[1,1,1] neg_lo:[0,0,1]
	v_pk_mul_f32 v[136:137], v[114:115], v[178:179] op_sel:[1,0] op_sel_hi:[0,0]
	v_pk_fma_f32 v[114:115], v[114:115], v[174:175], v[136:137] op_sel:[0,0,0] op_sel_hi:[1,0,1] neg_lo:[0,0,1]
	v_pk_mul_f32 v[136:137], v[116:117], v[178:179] op_sel:[1,1] op_sel_hi:[0,1]
	v_pk_fma_f32 v[116:117], v[116:117], v[174:175], v[136:137] op_sel:[0,1,0] op_sel_hi:[1,1,1] neg_lo:[0,0,1]
	v_pk_mul_f32 v[118:119], v[118:119], s[36:37] op_sel_hi:[1,0]
	v_pk_mul_f32 v[120:121], v[120:121], s[36:37] op_sel_hi:[1,0]
	v_pk_mul_f32 v[114:115], v[114:115], s[36:37] op_sel_hi:[1,0]
	v_pk_mul_f32 v[116:117], v[116:117], s[36:37] op_sel_hi:[1,0]
	v_cvt_pk_bf16_f32 v144, v118, v119
	v_cvt_pk_bf16_f32 v145, v120, v121
	v_cvt_pk_bf16_f32 v146, v114, v115
	v_cvt_pk_bf16_f32 v147, v116, v117
	ds_bpermute_b32 v218, v180, v140
	ds_bpermute_b32 v219, v180, v141
	ds_bpermute_b32 v220, v180, v142
	ds_bpermute_b32 v221, v180, v143
	ds_bpermute_b32 v222, v180, v144
	ds_bpermute_b32 v223, v180, v145
	ds_bpermute_b32 v224, v180, v146
	ds_bpermute_b32 v225, v180, v147
	s_add_u32 s8, s8, 0x800
	s_addc_u32 s9, s9, 0
	global_load_dwordx4 v[164:167], v131, s[8:9]
	global_load_dwordx4 v[168:171], v132, s[8:9]
	global_load_dwordx4 v[172:175], v131, s[8:9] offset:64
	global_load_dwordx4 v[176:179], v132, s[8:9] offset:64
	v_mul_f32_e32 v134, v109, v109
	v_fmac_f32_e32 v134, v108, v108
	v_fmac_f32_e32 v134, v110, v110
	v_fmac_f32_e32 v134, v111, v111
	v_fmac_f32_e32 v134, v104, v104
	v_fmac_f32_e32 v134, v105, v105
	v_fmac_f32_e32 v134, v106, v106
	v_fmac_f32_e32 v134, v107, v107
	v_fmac_f32_e32 v134, v100, v100
	v_fmac_f32_e32 v134, v101, v101
	v_pk_mul_f32 v[136:137], v[102:103], v[102:103]
	v_pk_mul_f32 v[138:139], v[96:97], v[96:97]
	v_add_f32_e32 v134, v136, v134
	v_add_f32_e32 v134, v137, v134
	v_add_f32_e32 v134, v138, v134
	v_pk_mul_f32 v[136:137], v[98:99], v[98:99]
	v_add_f32_e32 v134, v139, v134
	v_add_f32_e32 v134, v136, v134
	v_add_f32_e32 v134, v137, v134
	ds_swizzle_b32 v135, v134 offset:swizzle(SWAP,16)
	s_waitcnt lgkmcnt(0)
	v_add_f32_e32 v134, v134, v135
	v_mov_b32_e32 v135, v134
	s_nop 1
	v_permlane32_swap_b32 v134, v135
	s_nop 1
	v_add_f32_e32 v134, v134, v135
	v_fmamk_f32 v134, v134, 0x3c800000, v242
	v_rsq_f32_e32 v134, v134
	s_nop 0
	v_pk_mul_f32 v[136:137], v[134:135], v[148:149] op_sel_hi:[0,1]
	v_pk_mul_f32 v[108:109], v[108:109], v[136:137]
	v_pk_mul_f32 v[136:137], v[134:135], v[150:151] op_sel_hi:[0,1]
	v_pk_mul_f32 v[110:111], v[110:111], v[136:137]
	v_pk_mul_f32 v[136:137], v[134:135], v[152:153] op_sel_hi:[0,1]
	v_pk_mul_f32 v[104:105], v[104:105], v[136:137]
	v_pk_mul_f32 v[136:137], v[134:135], v[154:155] op_sel_hi:[0,1]
	v_pk_mul_f32 v[106:107], v[106:107], v[136:137]
	v_pk_mul_f32 v[136:137], v[134:135], v[156:157] op_sel_hi:[0,1]
	v_pk_mul_f32 v[100:101], v[100:101], v[136:137]
	v_pk_mul_f32 v[136:137], v[134:135], v[158:159] op_sel_hi:[0,1]
	v_pk_mul_f32 v[102:103], v[102:103], v[136:137]
	v_pk_mul_f32 v[136:137], v[134:135], v[160:161] op_sel_hi:[0,1]
	v_pk_mul_f32 v[96:97], v[96:97], v[136:137]
	v_pk_mul_f32 v[136:137], v[134:135], v[162:163] op_sel_hi:[0,1]
	v_pk_mul_f32 v[98:99], v[98:99], v[136:137]
	s_waitcnt vmcnt(4)
	v_pk_mul_f32 v[136:137], v[108:109], v[206:207] op_sel:[1,0] op_sel_hi:[0,0]
	v_pk_fma_f32 v[108:109], v[108:109], v[202:203], v[136:137] op_sel:[0,0,0] op_sel_hi:[1,0,1] neg_lo:[0,0,1]
	v_pk_mul_f32 v[136:137], v[110:111], v[206:207] op_sel:[1,1] op_sel_hi:[0,1]
	v_pk_fma_f32 v[110:111], v[110:111], v[202:203], v[136:137] op_sel:[0,1,0] op_sel_hi:[1,1,1] neg_lo:[0,0,1]
	v_pk_mul_f32 v[136:137], v[104:105], v[208:209] op_sel:[1,0] op_sel_hi:[0,0]
	v_pk_fma_f32 v[104:105], v[104:105], v[204:205], v[136:137] op_sel:[0,0,0] op_sel_hi:[1,0,1] neg_lo:[0,0,1]
	v_pk_mul_f32 v[136:137], v[106:107], v[208:209] op_sel:[1,1] op_sel_hi:[0,1]
	v_pk_fma_f32 v[106:107], v[106:107], v[204:205], v[136:137] op_sel:[0,1,0] op_sel_hi:[1,1,1] neg_lo:[0,0,1]
	v_pk_mul_f32 v[108:109], v[108:109], s[36:37] op_sel_hi:[1,0]
	v_pk_mul_f32 v[110:111], v[110:111], s[36:37] op_sel_hi:[1,0]
	v_pk_mul_f32 v[104:105], v[104:105], s[36:37] op_sel_hi:[1,0]
	v_pk_mul_f32 v[106:107], v[106:107], s[36:37] op_sel_hi:[1,0]
	v_cvt_pk_bf16_f32 v140, v108, v109
	v_cvt_pk_bf16_f32 v141, v110, v111
	v_cvt_pk_bf16_f32 v142, v104, v105
	v_cvt_pk_bf16_f32 v143, v106, v107
	v_pk_mul_f32 v[136:137], v[100:101], v[214:215] op_sel:[1,0] op_sel_hi:[0,0]
	v_pk_fma_f32 v[100:101], v[100:101], v[210:211], v[136:137] op_sel:[0,0,0] op_sel_hi:[1,0,1] neg_lo:[0,0,1]
	v_pk_mul_f32 v[136:137], v[102:103], v[214:215] op_sel:[1,1] op_sel_hi:[0,1]
	v_pk_fma_f32 v[102:103], v[102:103], v[210:211], v[136:137] op_sel:[0,1,0] op_sel_hi:[1,1,1] neg_lo:[0,0,1]
	v_pk_mul_f32 v[136:137], v[96:97], v[216:217] op_sel:[1,0] op_sel_hi:[0,0]
	v_pk_fma_f32 v[96:97], v[96:97], v[212:213], v[136:137] op_sel:[0,0,0] op_sel_hi:[1,0,1] neg_lo:[0,0,1]
	v_pk_mul_f32 v[136:137], v[98:99], v[216:217] op_sel:[1,1] op_sel_hi:[0,1]
	v_pk_fma_f32 v[98:99], v[98:99], v[212:213], v[136:137] op_sel:[0,1,0] op_sel_hi:[1,1,1] neg_lo:[0,0,1]
	v_pk_mul_f32 v[100:101], v[100:101], s[36:37] op_sel_hi:[1,0]
	v_pk_mul_f32 v[102:103], v[102:103], s[36:37] op_sel_hi:[1,0]
	v_pk_mul_f32 v[96:97], v[96:97], s[36:37] op_sel_hi:[1,0]
	v_pk_mul_f32 v[98:99], v[98:99], s[36:37] op_sel_hi:[1,0]
	v_cvt_pk_bf16_f32 v144, v100, v101
	v_cvt_pk_bf16_f32 v145, v102, v103
	v_cvt_pk_bf16_f32 v146, v96, v97
	v_cvt_pk_bf16_f32 v147, v98, v99
	s_waitcnt lgkmcnt(0)
	global_store_dwordx4 v130, v[218:221], s[6:7] nt
	global_store_dwordx4 v130, v[222:225], s[6:7] offset:64 nt
	s_add_u32 s6, s6, s33
	s_addc_u32 s7, s7, 0
	ds_bpermute_b32 v226, v180, v140
	ds_bpermute_b32 v227, v180, v141
	ds_bpermute_b32 v228, v180, v142
	ds_bpermute_b32 v229, v180, v143
	ds_bpermute_b32 v230, v180, v144
	ds_bpermute_b32 v231, v180, v145
	ds_bpermute_b32 v232, v180, v146
	ds_bpermute_b32 v233, v180, v147
	s_add_u32 s8, s8, 0x800
	s_addc_u32 s9, s9, 0
	global_load_dwordx4 v[202:205], v131, s[8:9]
	global_load_dwordx4 v[206:209], v132, s[8:9]
	global_load_dwordx4 v[210:213], v131, s[8:9] offset:64
	global_load_dwordx4 v[214:217], v132, s[8:9] offset:64
	v_mul_f32_e32 v134, v93, v93
	v_fmac_f32_e32 v134, v92, v92
	v_fmac_f32_e32 v134, v94, v94
	v_fmac_f32_e32 v134, v95, v95
	v_fmac_f32_e32 v134, v88, v88
	v_fmac_f32_e32 v134, v89, v89
	v_fmac_f32_e32 v134, v90, v90
	v_fmac_f32_e32 v134, v91, v91
	v_fmac_f32_e32 v134, v84, v84
	v_fmac_f32_e32 v134, v85, v85
	v_pk_mul_f32 v[136:137], v[86:87], v[86:87]
	v_pk_mul_f32 v[138:139], v[80:81], v[80:81]
	v_add_f32_e32 v134, v136, v134
	v_add_f32_e32 v134, v137, v134
	v_add_f32_e32 v134, v138, v134
	v_pk_mul_f32 v[136:137], v[82:83], v[82:83]
	v_add_f32_e32 v134, v139, v134
	v_add_f32_e32 v134, v136, v134
	v_add_f32_e32 v134, v137, v134
	ds_swizzle_b32 v135, v134 offset:swizzle(SWAP,16)
	s_waitcnt lgkmcnt(0)
	v_add_f32_e32 v134, v134, v135
	v_mov_b32_e32 v135, v134
	s_nop 1
	v_permlane32_swap_b32 v134, v135
	s_nop 1
	v_add_f32_e32 v134, v134, v135
	v_fmamk_f32 v134, v134, 0x3c800000, v242
	v_rsq_f32_e32 v134, v134
	s_nop 0
	v_pk_mul_f32 v[136:137], v[134:135], v[148:149] op_sel_hi:[0,1]
	v_pk_mul_f32 v[92:93], v[92:93], v[136:137]
	v_pk_mul_f32 v[136:137], v[134:135], v[150:151] op_sel_hi:[0,1]
	v_pk_mul_f32 v[94:95], v[94:95], v[136:137]
	v_pk_mul_f32 v[136:137], v[134:135], v[152:153] op_sel_hi:[0,1]
	v_pk_mul_f32 v[88:89], v[88:89], v[136:137]
	v_pk_mul_f32 v[136:137], v[134:135], v[154:155] op_sel_hi:[0,1]
	v_pk_mul_f32 v[90:91], v[90:91], v[136:137]
	v_pk_mul_f32 v[136:137], v[134:135], v[156:157] op_sel_hi:[0,1]
	v_pk_mul_f32 v[84:85], v[84:85], v[136:137]
	v_pk_mul_f32 v[136:137], v[134:135], v[158:159] op_sel_hi:[0,1]
	v_pk_mul_f32 v[86:87], v[86:87], v[136:137]
	v_pk_mul_f32 v[136:137], v[134:135], v[160:161] op_sel_hi:[0,1]
	v_pk_mul_f32 v[80:81], v[80:81], v[136:137]
	v_pk_mul_f32 v[136:137], v[134:135], v[162:163] op_sel_hi:[0,1]
	v_pk_mul_f32 v[82:83], v[82:83], v[136:137]
	s_waitcnt vmcnt(6)
	v_pk_mul_f32 v[136:137], v[92:93], v[168:169] op_sel:[1,0] op_sel_hi:[0,0]
	v_pk_fma_f32 v[92:93], v[92:93], v[164:165], v[136:137] op_sel:[0,0,0] op_sel_hi:[1,0,1] neg_lo:[0,0,1]
	v_pk_mul_f32 v[136:137], v[94:95], v[168:169] op_sel:[1,1] op_sel_hi:[0,1]
	v_pk_fma_f32 v[94:95], v[94:95], v[164:165], v[136:137] op_sel:[0,1,0] op_sel_hi:[1,1,1] neg_lo:[0,0,1]
	v_pk_mul_f32 v[136:137], v[88:89], v[170:171] op_sel:[1,0] op_sel_hi:[0,0]
	v_pk_fma_f32 v[88:89], v[88:89], v[166:167], v[136:137] op_sel:[0,0,0] op_sel_hi:[1,0,1] neg_lo:[0,0,1]
	v_pk_mul_f32 v[136:137], v[90:91], v[170:171] op_sel:[1,1] op_sel_hi:[0,1]
	v_pk_fma_f32 v[90:91], v[90:91], v[166:167], v[136:137] op_sel:[0,1,0] op_sel_hi:[1,1,1] neg_lo:[0,0,1]
	v_pk_mul_f32 v[92:93], v[92:93], s[36:37] op_sel_hi:[1,0]
	v_pk_mul_f32 v[94:95], v[94:95], s[36:37] op_sel_hi:[1,0]
	v_pk_mul_f32 v[88:89], v[88:89], s[36:37] op_sel_hi:[1,0]
	v_pk_mul_f32 v[90:91], v[90:91], s[36:37] op_sel_hi:[1,0]
	v_cvt_pk_bf16_f32 v140, v92, v93
	v_cvt_pk_bf16_f32 v141, v94, v95
	v_cvt_pk_bf16_f32 v142, v88, v89
	v_cvt_pk_bf16_f32 v143, v90, v91
	v_pk_mul_f32 v[136:137], v[84:85], v[176:177] op_sel:[1,0] op_sel_hi:[0,0]
	v_pk_fma_f32 v[84:85], v[84:85], v[172:173], v[136:137] op_sel:[0,0,0] op_sel_hi:[1,0,1] neg_lo:[0,0,1]
	v_pk_mul_f32 v[136:137], v[86:87], v[176:177] op_sel:[1,1] op_sel_hi:[0,1]
	v_pk_fma_f32 v[86:87], v[86:87], v[172:173], v[136:137] op_sel:[0,1,0] op_sel_hi:[1,1,1] neg_lo:[0,0,1]
	v_pk_mul_f32 v[136:137], v[80:81], v[178:179] op_sel:[1,0] op_sel_hi:[0,0]
	v_pk_fma_f32 v[80:81], v[80:81], v[174:175], v[136:137] op_sel:[0,0,0] op_sel_hi:[1,0,1] neg_lo:[0,0,1]
	v_pk_mul_f32 v[136:137], v[82:83], v[178:179] op_sel:[1,1] op_sel_hi:[0,1]
	v_pk_fma_f32 v[82:83], v[82:83], v[174:175], v[136:137] op_sel:[0,1,0] op_sel_hi:[1,1,1] neg_lo:[0,0,1]
	v_pk_mul_f32 v[84:85], v[84:85], s[36:37] op_sel_hi:[1,0]
	v_pk_mul_f32 v[86:87], v[86:87], s[36:37] op_sel_hi:[1,0]
	v_pk_mul_f32 v[80:81], v[80:81], s[36:37] op_sel_hi:[1,0]
	v_pk_mul_f32 v[82:83], v[82:83], s[36:37] op_sel_hi:[1,0]
	v_cvt_pk_bf16_f32 v144, v84, v85
	v_cvt_pk_bf16_f32 v145, v86, v87
	v_cvt_pk_bf16_f32 v146, v80, v81
	v_cvt_pk_bf16_f32 v147, v82, v83
	s_waitcnt lgkmcnt(0)
	global_store_dwordx4 v130, v[226:229], s[6:7] nt
	global_store_dwordx4 v130, v[230:233], s[6:7] offset:64 nt
	s_add_u32 s6, s6, s33
	s_addc_u32 s7, s7, 0
	ds_bpermute_b32 v218, v180, v140
	ds_bpermute_b32 v219, v180, v141
	ds_bpermute_b32 v220, v180, v142
	ds_bpermute_b32 v221, v180, v143
	ds_bpermute_b32 v222, v180, v144
	ds_bpermute_b32 v223, v180, v145
	ds_bpermute_b32 v224, v180, v146
	ds_bpermute_b32 v225, v180, v147
	s_add_u32 s8, s8, 0x2800
	s_addc_u32 s9, s9, 0
	global_load_dwordx4 v[164:167], v131, s[8:9]
	global_load_dwordx4 v[168:171], v132, s[8:9]
	global_load_dwordx4 v[172:175], v131, s[8:9] offset:64
	global_load_dwordx4 v[176:179], v132, s[8:9] offset:64
	v_mul_f32_e32 v134, v77, v77
	v_fmac_f32_e32 v134, v76, v76
	v_fmac_f32_e32 v134, v78, v78
	v_fmac_f32_e32 v134, v79, v79
	v_fmac_f32_e32 v134, v72, v72
	v_fmac_f32_e32 v134, v73, v73
	v_fmac_f32_e32 v134, v74, v74
	v_fmac_f32_e32 v134, v75, v75
	v_fmac_f32_e32 v134, v68, v68
	v_fmac_f32_e32 v134, v69, v69
	v_pk_mul_f32 v[136:137], v[70:71], v[70:71]
	v_pk_mul_f32 v[138:139], v[64:65], v[64:65]
	v_add_f32_e32 v134, v136, v134
	v_add_f32_e32 v134, v137, v134
	v_add_f32_e32 v134, v138, v134
	v_pk_mul_f32 v[136:137], v[66:67], v[66:67]
	v_add_f32_e32 v134, v139, v134
	v_add_f32_e32 v134, v136, v134
	v_add_f32_e32 v134, v137, v134
	ds_swizzle_b32 v135, v134 offset:swizzle(SWAP,16)
	s_waitcnt lgkmcnt(0)
	v_add_f32_e32 v134, v134, v135
	v_mov_b32_e32 v135, v134
	s_nop 1
	v_permlane32_swap_b32 v134, v135
	s_nop 1
	v_add_f32_e32 v134, v134, v135
	v_fmamk_f32 v134, v134, 0x3c800000, v242
	v_rsq_f32_e32 v134, v134
	s_nop 0
	v_pk_mul_f32 v[136:137], v[134:135], v[148:149] op_sel_hi:[0,1]
	v_pk_mul_f32 v[76:77], v[76:77], v[136:137]
	v_pk_mul_f32 v[136:137], v[134:135], v[150:151] op_sel_hi:[0,1]
	v_pk_mul_f32 v[78:79], v[78:79], v[136:137]
	v_pk_mul_f32 v[136:137], v[134:135], v[152:153] op_sel_hi:[0,1]
	v_pk_mul_f32 v[72:73], v[72:73], v[136:137]
	v_pk_mul_f32 v[136:137], v[134:135], v[154:155] op_sel_hi:[0,1]
	v_pk_mul_f32 v[74:75], v[74:75], v[136:137]
	v_pk_mul_f32 v[136:137], v[134:135], v[156:157] op_sel_hi:[0,1]
	v_pk_mul_f32 v[68:69], v[68:69], v[136:137]
	v_pk_mul_f32 v[136:137], v[134:135], v[158:159] op_sel_hi:[0,1]
	v_pk_mul_f32 v[70:71], v[70:71], v[136:137]
	v_pk_mul_f32 v[136:137], v[134:135], v[160:161] op_sel_hi:[0,1]
	v_pk_mul_f32 v[64:65], v[64:65], v[136:137]
	v_pk_mul_f32 v[136:137], v[134:135], v[162:163] op_sel_hi:[0,1]
	v_pk_mul_f32 v[66:67], v[66:67], v[136:137]
	s_waitcnt vmcnt(6)
	v_pk_mul_f32 v[136:137], v[76:77], v[206:207] op_sel:[1,0] op_sel_hi:[0,0]
	v_pk_fma_f32 v[76:77], v[76:77], v[202:203], v[136:137] op_sel:[0,0,0] op_sel_hi:[1,0,1] neg_lo:[0,0,1]
	v_pk_mul_f32 v[136:137], v[78:79], v[206:207] op_sel:[1,1] op_sel_hi:[0,1]
	v_pk_fma_f32 v[78:79], v[78:79], v[202:203], v[136:137] op_sel:[0,1,0] op_sel_hi:[1,1,1] neg_lo:[0,0,1]
	v_pk_mul_f32 v[136:137], v[72:73], v[208:209] op_sel:[1,0] op_sel_hi:[0,0]
	v_pk_fma_f32 v[72:73], v[72:73], v[204:205], v[136:137] op_sel:[0,0,0] op_sel_hi:[1,0,1] neg_lo:[0,0,1]
	v_pk_mul_f32 v[136:137], v[74:75], v[208:209] op_sel:[1,1] op_sel_hi:[0,1]
	v_pk_fma_f32 v[74:75], v[74:75], v[204:205], v[136:137] op_sel:[0,1,0] op_sel_hi:[1,1,1] neg_lo:[0,0,1]
	v_pk_mul_f32 v[76:77], v[76:77], s[36:37] op_sel_hi:[1,0]
	v_pk_mul_f32 v[78:79], v[78:79], s[36:37] op_sel_hi:[1,0]
	v_pk_mul_f32 v[72:73], v[72:73], s[36:37] op_sel_hi:[1,0]
	v_pk_mul_f32 v[74:75], v[74:75], s[36:37] op_sel_hi:[1,0]
	v_cvt_pk_bf16_f32 v140, v76, v77
	v_cvt_pk_bf16_f32 v141, v78, v79
	v_cvt_pk_bf16_f32 v142, v72, v73
	v_cvt_pk_bf16_f32 v143, v74, v75
	v_pk_mul_f32 v[136:137], v[68:69], v[214:215] op_sel:[1,0] op_sel_hi:[0,0]
	v_pk_fma_f32 v[68:69], v[68:69], v[210:211], v[136:137] op_sel:[0,0,0] op_sel_hi:[1,0,1] neg_lo:[0,0,1]
	v_pk_mul_f32 v[136:137], v[70:71], v[214:215] op_sel:[1,1] op_sel_hi:[0,1]
	v_pk_fma_f32 v[70:71], v[70:71], v[210:211], v[136:137] op_sel:[0,1,0] op_sel_hi:[1,1,1] neg_lo:[0,0,1]
	v_pk_mul_f32 v[136:137], v[64:65], v[216:217] op_sel:[1,0] op_sel_hi:[0,0]
	v_pk_fma_f32 v[64:65], v[64:65], v[212:213], v[136:137] op_sel:[0,0,0] op_sel_hi:[1,0,1] neg_lo:[0,0,1]
	v_pk_mul_f32 v[136:137], v[66:67], v[216:217] op_sel:[1,1] op_sel_hi:[0,1]
	v_pk_fma_f32 v[66:67], v[66:67], v[212:213], v[136:137] op_sel:[0,1,0] op_sel_hi:[1,1,1] neg_lo:[0,0,1]
	v_pk_mul_f32 v[68:69], v[68:69], s[36:37] op_sel_hi:[1,0]
	v_pk_mul_f32 v[70:71], v[70:71], s[36:37] op_sel_hi:[1,0]
	v_pk_mul_f32 v[64:65], v[64:65], s[36:37] op_sel_hi:[1,0]
	v_pk_mul_f32 v[66:67], v[66:67], s[36:37] op_sel_hi:[1,0]
	v_cvt_pk_bf16_f32 v144, v68, v69
	v_cvt_pk_bf16_f32 v145, v70, v71
	v_cvt_pk_bf16_f32 v146, v64, v65
	v_cvt_pk_bf16_f32 v147, v66, v67
	s_waitcnt lgkmcnt(0)
	global_store_dwordx4 v130, v[218:221], s[6:7] nt
	global_store_dwordx4 v130, v[222:225], s[6:7] offset:64 nt
	s_add_u32 s6, s6, s33
	s_addc_u32 s7, s7, 0
	ds_bpermute_b32 v226, v180, v140
	ds_bpermute_b32 v227, v180, v141
	ds_bpermute_b32 v228, v180, v142
	ds_bpermute_b32 v229, v180, v143
	ds_bpermute_b32 v230, v180, v144
	ds_bpermute_b32 v231, v180, v145
	ds_bpermute_b32 v232, v180, v146
	ds_bpermute_b32 v233, v180, v147
	s_add_u32 s8, s8, 0x800
	s_addc_u32 s9, s9, 0
	global_load_dwordx4 v[202:205], v131, s[8:9]
	global_load_dwordx4 v[206:209], v132, s[8:9]
	global_load_dwordx4 v[210:213], v131, s[8:9] offset:64
	global_load_dwordx4 v[214:217], v132, s[8:9] offset:64
	v_mul_f32_e32 v134, v61, v61
	v_fmac_f32_e32 v134, v60, v60
	v_fmac_f32_e32 v134, v62, v62
	v_fmac_f32_e32 v134, v63, v63
	v_fmac_f32_e32 v134, v56, v56
	v_fmac_f32_e32 v134, v57, v57
	v_fmac_f32_e32 v134, v58, v58
	v_fmac_f32_e32 v134, v59, v59
	v_fmac_f32_e32 v134, v52, v52
	v_fmac_f32_e32 v134, v53, v53
	v_pk_mul_f32 v[136:137], v[54:55], v[54:55]
	v_pk_mul_f32 v[138:139], v[48:49], v[48:49]
	v_add_f32_e32 v134, v136, v134
	v_add_f32_e32 v134, v137, v134
	v_add_f32_e32 v134, v138, v134
	v_pk_mul_f32 v[136:137], v[50:51], v[50:51]
	v_add_f32_e32 v134, v139, v134
	v_add_f32_e32 v134, v136, v134
	v_add_f32_e32 v134, v137, v134
	ds_swizzle_b32 v135, v134 offset:swizzle(SWAP,16)
	s_waitcnt lgkmcnt(0)
	v_add_f32_e32 v134, v134, v135
	v_mov_b32_e32 v135, v134
	s_nop 1
	v_permlane32_swap_b32 v134, v135
	s_nop 1
	v_add_f32_e32 v134, v134, v135
	v_fmamk_f32 v134, v134, 0x3c800000, v242
	v_rsq_f32_e32 v134, v134
	s_nop 0
	v_pk_mul_f32 v[136:137], v[134:135], v[148:149] op_sel_hi:[0,1]
	v_pk_mul_f32 v[60:61], v[60:61], v[136:137]
	v_pk_mul_f32 v[136:137], v[134:135], v[150:151] op_sel_hi:[0,1]
	v_pk_mul_f32 v[62:63], v[62:63], v[136:137]
	v_pk_mul_f32 v[136:137], v[134:135], v[152:153] op_sel_hi:[0,1]
	v_pk_mul_f32 v[56:57], v[56:57], v[136:137]
	v_pk_mul_f32 v[136:137], v[134:135], v[154:155] op_sel_hi:[0,1]
	v_pk_mul_f32 v[58:59], v[58:59], v[136:137]
	v_pk_mul_f32 v[136:137], v[134:135], v[156:157] op_sel_hi:[0,1]
	v_pk_mul_f32 v[52:53], v[52:53], v[136:137]
	v_pk_mul_f32 v[136:137], v[134:135], v[158:159] op_sel_hi:[0,1]
	v_pk_mul_f32 v[54:55], v[54:55], v[136:137]
	v_pk_mul_f32 v[136:137], v[134:135], v[160:161] op_sel_hi:[0,1]
	v_pk_mul_f32 v[48:49], v[48:49], v[136:137]
	v_pk_mul_f32 v[136:137], v[134:135], v[162:163] op_sel_hi:[0,1]
	v_pk_mul_f32 v[50:51], v[50:51], v[136:137]
	s_waitcnt vmcnt(6)
	v_pk_mul_f32 v[136:137], v[60:61], v[168:169] op_sel:[1,0] op_sel_hi:[0,0]
	v_pk_fma_f32 v[60:61], v[60:61], v[164:165], v[136:137] op_sel:[0,0,0] op_sel_hi:[1,0,1] neg_lo:[0,0,1]
	v_pk_mul_f32 v[136:137], v[62:63], v[168:169] op_sel:[1,1] op_sel_hi:[0,1]
	v_pk_fma_f32 v[62:63], v[62:63], v[164:165], v[136:137] op_sel:[0,1,0] op_sel_hi:[1,1,1] neg_lo:[0,0,1]
	v_pk_mul_f32 v[136:137], v[56:57], v[170:171] op_sel:[1,0] op_sel_hi:[0,0]
	v_pk_fma_f32 v[56:57], v[56:57], v[166:167], v[136:137] op_sel:[0,0,0] op_sel_hi:[1,0,1] neg_lo:[0,0,1]
	v_pk_mul_f32 v[136:137], v[58:59], v[170:171] op_sel:[1,1] op_sel_hi:[0,1]
	v_pk_fma_f32 v[58:59], v[58:59], v[166:167], v[136:137] op_sel:[0,1,0] op_sel_hi:[1,1,1] neg_lo:[0,0,1]
	v_pk_mul_f32 v[60:61], v[60:61], s[36:37] op_sel_hi:[1,0]
	v_pk_mul_f32 v[62:63], v[62:63], s[36:37] op_sel_hi:[1,0]
	v_pk_mul_f32 v[56:57], v[56:57], s[36:37] op_sel_hi:[1,0]
	v_pk_mul_f32 v[58:59], v[58:59], s[36:37] op_sel_hi:[1,0]
	v_cvt_pk_bf16_f32 v140, v60, v61
	v_cvt_pk_bf16_f32 v141, v62, v63
	v_cvt_pk_bf16_f32 v142, v56, v57
	v_cvt_pk_bf16_f32 v143, v58, v59
	v_pk_mul_f32 v[136:137], v[52:53], v[176:177] op_sel:[1,0] op_sel_hi:[0,0]
	v_pk_fma_f32 v[52:53], v[52:53], v[172:173], v[136:137] op_sel:[0,0,0] op_sel_hi:[1,0,1] neg_lo:[0,0,1]
	v_pk_mul_f32 v[136:137], v[54:55], v[176:177] op_sel:[1,1] op_sel_hi:[0,1]
	v_pk_fma_f32 v[54:55], v[54:55], v[172:173], v[136:137] op_sel:[0,1,0] op_sel_hi:[1,1,1] neg_lo:[0,0,1]
	v_pk_mul_f32 v[136:137], v[48:49], v[178:179] op_sel:[1,0] op_sel_hi:[0,0]
	v_pk_fma_f32 v[48:49], v[48:49], v[174:175], v[136:137] op_sel:[0,0,0] op_sel_hi:[1,0,1] neg_lo:[0,0,1]
	v_pk_mul_f32 v[136:137], v[50:51], v[178:179] op_sel:[1,1] op_sel_hi:[0,1]
	v_pk_fma_f32 v[50:51], v[50:51], v[174:175], v[136:137] op_sel:[0,1,0] op_sel_hi:[1,1,1] neg_lo:[0,0,1]
	v_pk_mul_f32 v[52:53], v[52:53], s[36:37] op_sel_hi:[1,0]
	v_pk_mul_f32 v[54:55], v[54:55], s[36:37] op_sel_hi:[1,0]
	v_pk_mul_f32 v[48:49], v[48:49], s[36:37] op_sel_hi:[1,0]
	v_pk_mul_f32 v[50:51], v[50:51], s[36:37] op_sel_hi:[1,0]
	v_cvt_pk_bf16_f32 v144, v52, v53
	v_cvt_pk_bf16_f32 v145, v54, v55
	v_cvt_pk_bf16_f32 v146, v48, v49
	v_cvt_pk_bf16_f32 v147, v50, v51
	s_waitcnt lgkmcnt(0)
	global_store_dwordx4 v130, v[226:229], s[6:7] nt
	global_store_dwordx4 v130, v[230:233], s[6:7] offset:64 nt
	s_add_u32 s6, s6, s34
	s_addc_u32 s7, s7, 0
	ds_bpermute_b32 v218, v180, v140
	ds_bpermute_b32 v219, v180, v141
	ds_bpermute_b32 v220, v180, v142
	ds_bpermute_b32 v221, v180, v143
	ds_bpermute_b32 v222, v180, v144
	ds_bpermute_b32 v223, v180, v145
	ds_bpermute_b32 v224, v180, v146
	ds_bpermute_b32 v225, v180, v147
	s_add_u32 s8, s8, 0x800
	s_addc_u32 s9, s9, 0
	global_load_dwordx4 v[164:167], v131, s[8:9]
	global_load_dwordx4 v[168:171], v132, s[8:9]
	global_load_dwordx4 v[172:175], v131, s[8:9] offset:64
	global_load_dwordx4 v[176:179], v132, s[8:9] offset:64
	v_mul_f32_e32 v134, v45, v45
	v_fmac_f32_e32 v134, v44, v44
	v_fmac_f32_e32 v134, v46, v46
	v_fmac_f32_e32 v134, v47, v47
	v_fmac_f32_e32 v134, v40, v40
	v_fmac_f32_e32 v134, v41, v41
	v_fmac_f32_e32 v134, v42, v42
	v_fmac_f32_e32 v134, v43, v43
	v_fmac_f32_e32 v134, v36, v36
	v_fmac_f32_e32 v134, v37, v37
	v_pk_mul_f32 v[136:137], v[38:39], v[38:39]
	v_pk_mul_f32 v[138:139], v[32:33], v[32:33]
	v_add_f32_e32 v134, v136, v134
	v_add_f32_e32 v134, v137, v134
	v_add_f32_e32 v134, v138, v134
	v_pk_mul_f32 v[136:137], v[34:35], v[34:35]
	v_add_f32_e32 v134, v139, v134
	v_add_f32_e32 v134, v136, v134
	v_add_f32_e32 v134, v137, v134
	ds_swizzle_b32 v135, v134 offset:swizzle(SWAP,16)
	s_waitcnt lgkmcnt(0)
	v_add_f32_e32 v134, v134, v135
	v_mov_b32_e32 v135, v134
	s_nop 1
	v_permlane32_swap_b32 v134, v135
	s_nop 1
	v_add_f32_e32 v134, v134, v135
	v_fmamk_f32 v134, v134, 0x3c800000, v242
	v_rsq_f32_e32 v134, v134
	s_nop 0
	v_pk_mul_f32 v[136:137], v[134:135], v[148:149] op_sel_hi:[0,1]
	v_pk_mul_f32 v[44:45], v[44:45], v[136:137]
	v_pk_mul_f32 v[136:137], v[134:135], v[150:151] op_sel_hi:[0,1]
	v_pk_mul_f32 v[46:47], v[46:47], v[136:137]
	v_pk_mul_f32 v[136:137], v[134:135], v[152:153] op_sel_hi:[0,1]
	v_pk_mul_f32 v[40:41], v[40:41], v[136:137]
	v_pk_mul_f32 v[136:137], v[134:135], v[154:155] op_sel_hi:[0,1]
	v_pk_mul_f32 v[42:43], v[42:43], v[136:137]
	v_pk_mul_f32 v[136:137], v[134:135], v[156:157] op_sel_hi:[0,1]
	v_pk_mul_f32 v[36:37], v[36:37], v[136:137]
	v_pk_mul_f32 v[136:137], v[134:135], v[158:159] op_sel_hi:[0,1]
	v_pk_mul_f32 v[38:39], v[38:39], v[136:137]
	v_pk_mul_f32 v[136:137], v[134:135], v[160:161] op_sel_hi:[0,1]
	v_pk_mul_f32 v[32:33], v[32:33], v[136:137]
	v_pk_mul_f32 v[136:137], v[134:135], v[162:163] op_sel_hi:[0,1]
	v_pk_mul_f32 v[34:35], v[34:35], v[136:137]
	s_waitcnt vmcnt(6)
	v_pk_mul_f32 v[136:137], v[44:45], v[206:207] op_sel:[1,0] op_sel_hi:[0,0]
	v_pk_fma_f32 v[44:45], v[44:45], v[202:203], v[136:137] op_sel:[0,0,0] op_sel_hi:[1,0,1] neg_lo:[0,0,1]
	v_pk_mul_f32 v[136:137], v[46:47], v[206:207] op_sel:[1,1] op_sel_hi:[0,1]
	v_pk_fma_f32 v[46:47], v[46:47], v[202:203], v[136:137] op_sel:[0,1,0] op_sel_hi:[1,1,1] neg_lo:[0,0,1]
	v_pk_mul_f32 v[136:137], v[40:41], v[208:209] op_sel:[1,0] op_sel_hi:[0,0]
	v_pk_fma_f32 v[40:41], v[40:41], v[204:205], v[136:137] op_sel:[0,0,0] op_sel_hi:[1,0,1] neg_lo:[0,0,1]
	v_pk_mul_f32 v[136:137], v[42:43], v[208:209] op_sel:[1,1] op_sel_hi:[0,1]
	v_pk_fma_f32 v[42:43], v[42:43], v[204:205], v[136:137] op_sel:[0,1,0] op_sel_hi:[1,1,1] neg_lo:[0,0,1]
	v_pk_mul_f32 v[44:45], v[44:45], s[36:37] op_sel_hi:[1,0]
	v_pk_mul_f32 v[46:47], v[46:47], s[36:37] op_sel_hi:[1,0]
	v_pk_mul_f32 v[40:41], v[40:41], s[36:37] op_sel_hi:[1,0]
	v_pk_mul_f32 v[42:43], v[42:43], s[36:37] op_sel_hi:[1,0]
	v_cvt_pk_bf16_f32 v140, v44, v45
	v_cvt_pk_bf16_f32 v141, v46, v47
	v_cvt_pk_bf16_f32 v142, v40, v41
	v_cvt_pk_bf16_f32 v143, v42, v43
	v_pk_mul_f32 v[136:137], v[36:37], v[214:215] op_sel:[1,0] op_sel_hi:[0,0]
	v_pk_fma_f32 v[36:37], v[36:37], v[210:211], v[136:137] op_sel:[0,0,0] op_sel_hi:[1,0,1] neg_lo:[0,0,1]
	v_pk_mul_f32 v[136:137], v[38:39], v[214:215] op_sel:[1,1] op_sel_hi:[0,1]
	v_pk_fma_f32 v[38:39], v[38:39], v[210:211], v[136:137] op_sel:[0,1,0] op_sel_hi:[1,1,1] neg_lo:[0,0,1]
	v_pk_mul_f32 v[136:137], v[32:33], v[216:217] op_sel:[1,0] op_sel_hi:[0,0]
	v_pk_fma_f32 v[32:33], v[32:33], v[212:213], v[136:137] op_sel:[0,0,0] op_sel_hi:[1,0,1] neg_lo:[0,0,1]
	v_pk_mul_f32 v[136:137], v[34:35], v[216:217] op_sel:[1,1] op_sel_hi:[0,1]
	v_pk_fma_f32 v[34:35], v[34:35], v[212:213], v[136:137] op_sel:[0,1,0] op_sel_hi:[1,1,1] neg_lo:[0,0,1]
	v_pk_mul_f32 v[36:37], v[36:37], s[36:37] op_sel_hi:[1,0]
	v_pk_mul_f32 v[38:39], v[38:39], s[36:37] op_sel_hi:[1,0]
	v_pk_mul_f32 v[32:33], v[32:33], s[36:37] op_sel_hi:[1,0]
	v_pk_mul_f32 v[34:35], v[34:35], s[36:37] op_sel_hi:[1,0]
	v_cvt_pk_bf16_f32 v144, v36, v37
	v_cvt_pk_bf16_f32 v145, v38, v39
	v_cvt_pk_bf16_f32 v146, v32, v33
	v_cvt_pk_bf16_f32 v147, v34, v35
	s_waitcnt lgkmcnt(0)
	global_store_dwordx4 v130, v[218:221], s[6:7] nt
	global_store_dwordx4 v130, v[222:225], s[6:7] offset:64 nt
	s_add_u32 s6, s6, s33
	s_addc_u32 s7, s7, 0
	ds_bpermute_b32 v226, v180, v140
	ds_bpermute_b32 v227, v180, v141
	ds_bpermute_b32 v228, v180, v142
	ds_bpermute_b32 v229, v180, v143
	ds_bpermute_b32 v230, v180, v144
	ds_bpermute_b32 v231, v180, v145
	ds_bpermute_b32 v232, v180, v146
	ds_bpermute_b32 v233, v180, v147
	s_add_u32 s8, s8, 0x800
	s_addc_u32 s9, s9, 0
	global_load_dwordx4 v[202:205], v131, s[8:9]
	global_load_dwordx4 v[206:209], v132, s[8:9]
	global_load_dwordx4 v[210:213], v131, s[8:9] offset:64
	global_load_dwordx4 v[214:217], v132, s[8:9] offset:64
	v_mul_f32_e32 v134, v29, v29
	v_fmac_f32_e32 v134, v28, v28
	v_fmac_f32_e32 v134, v30, v30
	v_fmac_f32_e32 v134, v31, v31
	v_fmac_f32_e32 v134, v24, v24
	v_fmac_f32_e32 v134, v25, v25
	v_fmac_f32_e32 v134, v26, v26
	v_fmac_f32_e32 v134, v27, v27
	v_fmac_f32_e32 v134, v20, v20
	v_fmac_f32_e32 v134, v21, v21
	v_pk_mul_f32 v[136:137], v[22:23], v[22:23]
	v_pk_mul_f32 v[138:139], v[16:17], v[16:17]
	v_add_f32_e32 v134, v136, v134
	v_add_f32_e32 v134, v137, v134
	v_add_f32_e32 v134, v138, v134
	v_pk_mul_f32 v[136:137], v[18:19], v[18:19]
	v_add_f32_e32 v134, v139, v134
	v_add_f32_e32 v134, v136, v134
	v_add_f32_e32 v134, v137, v134
	ds_swizzle_b32 v135, v134 offset:swizzle(SWAP,16)
	s_waitcnt lgkmcnt(0)
	v_add_f32_e32 v134, v134, v135
	v_mov_b32_e32 v135, v134
	s_nop 1
	v_permlane32_swap_b32 v134, v135
	s_nop 1
	v_add_f32_e32 v134, v134, v135
	v_fmamk_f32 v134, v134, 0x3c800000, v242
	v_rsq_f32_e32 v134, v134
	s_nop 0
	v_pk_mul_f32 v[136:137], v[134:135], v[148:149] op_sel_hi:[0,1]
	v_pk_mul_f32 v[28:29], v[28:29], v[136:137]
	v_pk_mul_f32 v[136:137], v[134:135], v[150:151] op_sel_hi:[0,1]
	v_pk_mul_f32 v[30:31], v[30:31], v[136:137]
	v_pk_mul_f32 v[136:137], v[134:135], v[152:153] op_sel_hi:[0,1]
	v_pk_mul_f32 v[24:25], v[24:25], v[136:137]
	v_pk_mul_f32 v[136:137], v[134:135], v[154:155] op_sel_hi:[0,1]
	v_pk_mul_f32 v[26:27], v[26:27], v[136:137]
	v_pk_mul_f32 v[136:137], v[134:135], v[156:157] op_sel_hi:[0,1]
	v_pk_mul_f32 v[20:21], v[20:21], v[136:137]
	v_pk_mul_f32 v[136:137], v[134:135], v[158:159] op_sel_hi:[0,1]
	v_pk_mul_f32 v[22:23], v[22:23], v[136:137]
	v_pk_mul_f32 v[136:137], v[134:135], v[160:161] op_sel_hi:[0,1]
	v_pk_mul_f32 v[16:17], v[16:17], v[136:137]
	v_pk_mul_f32 v[136:137], v[134:135], v[162:163] op_sel_hi:[0,1]
	v_pk_mul_f32 v[18:19], v[18:19], v[136:137]
	s_waitcnt vmcnt(6)
	v_pk_mul_f32 v[136:137], v[28:29], v[168:169] op_sel:[1,0] op_sel_hi:[0,0]
	v_pk_fma_f32 v[28:29], v[28:29], v[164:165], v[136:137] op_sel:[0,0,0] op_sel_hi:[1,0,1] neg_lo:[0,0,1]
	v_pk_mul_f32 v[136:137], v[30:31], v[168:169] op_sel:[1,1] op_sel_hi:[0,1]
	v_pk_fma_f32 v[30:31], v[30:31], v[164:165], v[136:137] op_sel:[0,1,0] op_sel_hi:[1,1,1] neg_lo:[0,0,1]
	v_pk_mul_f32 v[136:137], v[24:25], v[170:171] op_sel:[1,0] op_sel_hi:[0,0]
	v_pk_fma_f32 v[24:25], v[24:25], v[166:167], v[136:137] op_sel:[0,0,0] op_sel_hi:[1,0,1] neg_lo:[0,0,1]
	v_pk_mul_f32 v[136:137], v[26:27], v[170:171] op_sel:[1,1] op_sel_hi:[0,1]
	v_pk_fma_f32 v[26:27], v[26:27], v[166:167], v[136:137] op_sel:[0,1,0] op_sel_hi:[1,1,1] neg_lo:[0,0,1]
	v_pk_mul_f32 v[28:29], v[28:29], s[36:37] op_sel_hi:[1,0]
	v_pk_mul_f32 v[30:31], v[30:31], s[36:37] op_sel_hi:[1,0]
	v_pk_mul_f32 v[24:25], v[24:25], s[36:37] op_sel_hi:[1,0]
	v_pk_mul_f32 v[26:27], v[26:27], s[36:37] op_sel_hi:[1,0]
	v_cvt_pk_bf16_f32 v140, v28, v29
	v_cvt_pk_bf16_f32 v141, v30, v31
	v_cvt_pk_bf16_f32 v142, v24, v25
	v_cvt_pk_bf16_f32 v143, v26, v27
	v_pk_mul_f32 v[136:137], v[20:21], v[176:177] op_sel:[1,0] op_sel_hi:[0,0]
	v_pk_fma_f32 v[20:21], v[20:21], v[172:173], v[136:137] op_sel:[0,0,0] op_sel_hi:[1,0,1] neg_lo:[0,0,1]
	v_pk_mul_f32 v[136:137], v[22:23], v[176:177] op_sel:[1,1] op_sel_hi:[0,1]
	v_pk_fma_f32 v[22:23], v[22:23], v[172:173], v[136:137] op_sel:[0,1,0] op_sel_hi:[1,1,1] neg_lo:[0,0,1]
	v_pk_mul_f32 v[136:137], v[16:17], v[178:179] op_sel:[1,0] op_sel_hi:[0,0]
	v_pk_fma_f32 v[16:17], v[16:17], v[174:175], v[136:137] op_sel:[0,0,0] op_sel_hi:[1,0,1] neg_lo:[0,0,1]
	v_pk_mul_f32 v[136:137], v[18:19], v[178:179] op_sel:[1,1] op_sel_hi:[0,1]
	v_pk_fma_f32 v[18:19], v[18:19], v[174:175], v[136:137] op_sel:[0,1,0] op_sel_hi:[1,1,1] neg_lo:[0,0,1]
	v_pk_mul_f32 v[20:21], v[20:21], s[36:37] op_sel_hi:[1,0]
	v_pk_mul_f32 v[22:23], v[22:23], s[36:37] op_sel_hi:[1,0]
	v_pk_mul_f32 v[16:17], v[16:17], s[36:37] op_sel_hi:[1,0]
	v_pk_mul_f32 v[18:19], v[18:19], s[36:37] op_sel_hi:[1,0]
	v_cvt_pk_bf16_f32 v144, v20, v21
	v_cvt_pk_bf16_f32 v145, v22, v23
	v_cvt_pk_bf16_f32 v146, v16, v17
	v_cvt_pk_bf16_f32 v147, v18, v19
	s_waitcnt lgkmcnt(0)
	global_store_dwordx4 v130, v[226:229], s[6:7] nt
	global_store_dwordx4 v130, v[230:233], s[6:7] offset:64 nt
	s_add_u32 s6, s6, s33
	s_addc_u32 s7, s7, 0
	ds_bpermute_b32 v218, v180, v140
	ds_bpermute_b32 v219, v180, v141
	ds_bpermute_b32 v220, v180, v142
	ds_bpermute_b32 v221, v180, v143
	ds_bpermute_b32 v222, v180, v144
	ds_bpermute_b32 v223, v180, v145
	ds_bpermute_b32 v224, v180, v146
	ds_bpermute_b32 v225, v180, v147
	v_mul_f32_e32 v134, v13, v13
	v_fmac_f32_e32 v134, v12, v12
	v_fmac_f32_e32 v134, v14, v14
	v_fmac_f32_e32 v134, v15, v15
	v_fmac_f32_e32 v134, v4, v4
	v_fmac_f32_e32 v134, v5, v5
	v_fmac_f32_e32 v134, v6, v6
	v_fmac_f32_e32 v134, v7, v7
	v_fmac_f32_e32 v134, v8, v8
	v_fmac_f32_e32 v134, v9, v9
	v_pk_mul_f32 v[136:137], v[10:11], v[10:11]
	v_pk_mul_f32 v[138:139], v[0:1], v[0:1]
	v_add_f32_e32 v134, v136, v134
	v_add_f32_e32 v134, v137, v134
	v_add_f32_e32 v134, v138, v134
	v_pk_mul_f32 v[136:137], v[2:3], v[2:3]
	v_add_f32_e32 v134, v139, v134
	v_add_f32_e32 v134, v136, v134
	v_add_f32_e32 v134, v137, v134
	ds_swizzle_b32 v135, v134 offset:swizzle(SWAP,16)
	s_waitcnt lgkmcnt(0)
	v_add_f32_e32 v134, v134, v135
	v_mov_b32_e32 v135, v134
	s_nop 1
	v_permlane32_swap_b32 v134, v135
	s_nop 1
	v_add_f32_e32 v134, v134, v135
	v_fmamk_f32 v134, v134, 0x3c800000, v242
	v_rsq_f32_e32 v134, v134
	s_nop 0
	v_pk_mul_f32 v[136:137], v[134:135], v[148:149] op_sel_hi:[0,1]
	v_pk_mul_f32 v[12:13], v[12:13], v[136:137]
	v_pk_mul_f32 v[136:137], v[134:135], v[150:151] op_sel_hi:[0,1]
	v_pk_mul_f32 v[14:15], v[14:15], v[136:137]
	v_pk_mul_f32 v[136:137], v[134:135], v[152:153] op_sel_hi:[0,1]
	v_pk_mul_f32 v[4:5], v[4:5], v[136:137]
	v_pk_mul_f32 v[136:137], v[134:135], v[154:155] op_sel_hi:[0,1]
	v_pk_mul_f32 v[6:7], v[6:7], v[136:137]
	v_pk_mul_f32 v[136:137], v[134:135], v[156:157] op_sel_hi:[0,1]
	v_pk_mul_f32 v[8:9], v[8:9], v[136:137]
	v_pk_mul_f32 v[136:137], v[134:135], v[158:159] op_sel_hi:[0,1]
	v_pk_mul_f32 v[10:11], v[10:11], v[136:137]
	v_pk_mul_f32 v[136:137], v[134:135], v[160:161] op_sel_hi:[0,1]
	v_pk_mul_f32 v[0:1], v[0:1], v[136:137]
	v_pk_mul_f32 v[136:137], v[134:135], v[162:163] op_sel_hi:[0,1]
	v_pk_mul_f32 v[2:3], v[2:3], v[136:137]
	s_waitcnt vmcnt(2)
	v_pk_mul_f32 v[136:137], v[12:13], v[206:207] op_sel:[1,0] op_sel_hi:[0,0]
	v_pk_fma_f32 v[12:13], v[12:13], v[202:203], v[136:137] op_sel:[0,0,0] op_sel_hi:[1,0,1] neg_lo:[0,0,1]
	v_pk_mul_f32 v[136:137], v[14:15], v[206:207] op_sel:[1,1] op_sel_hi:[0,1]
	v_pk_fma_f32 v[14:15], v[14:15], v[202:203], v[136:137] op_sel:[0,1,0] op_sel_hi:[1,1,1] neg_lo:[0,0,1]
	v_pk_mul_f32 v[136:137], v[4:5], v[208:209] op_sel:[1,0] op_sel_hi:[0,0]
	v_pk_fma_f32 v[4:5], v[4:5], v[204:205], v[136:137] op_sel:[0,0,0] op_sel_hi:[1,0,1] neg_lo:[0,0,1]
	v_pk_mul_f32 v[136:137], v[6:7], v[208:209] op_sel:[1,1] op_sel_hi:[0,1]
	v_pk_fma_f32 v[6:7], v[6:7], v[204:205], v[136:137] op_sel:[0,1,0] op_sel_hi:[1,1,1] neg_lo:[0,0,1]
	v_pk_mul_f32 v[12:13], v[12:13], s[36:37] op_sel_hi:[1,0]
	v_pk_mul_f32 v[14:15], v[14:15], s[36:37] op_sel_hi:[1,0]
	v_pk_mul_f32 v[4:5], v[4:5], s[36:37] op_sel_hi:[1,0]
	v_pk_mul_f32 v[6:7], v[6:7], s[36:37] op_sel_hi:[1,0]
	v_cvt_pk_bf16_f32 v140, v12, v13
	v_cvt_pk_bf16_f32 v141, v14, v15
	v_cvt_pk_bf16_f32 v142, v4, v5
	v_cvt_pk_bf16_f32 v143, v6, v7
	v_pk_mul_f32 v[136:137], v[8:9], v[214:215] op_sel:[1,0] op_sel_hi:[0,0]
	v_pk_fma_f32 v[8:9], v[8:9], v[210:211], v[136:137] op_sel:[0,0,0] op_sel_hi:[1,0,1] neg_lo:[0,0,1]
	v_pk_mul_f32 v[136:137], v[10:11], v[214:215] op_sel:[1,1] op_sel_hi:[0,1]
	v_pk_fma_f32 v[10:11], v[10:11], v[210:211], v[136:137] op_sel:[0,1,0] op_sel_hi:[1,1,1] neg_lo:[0,0,1]
	v_pk_mul_f32 v[136:137], v[0:1], v[216:217] op_sel:[1,0] op_sel_hi:[0,0]
	v_pk_fma_f32 v[0:1], v[0:1], v[212:213], v[136:137] op_sel:[0,0,0] op_sel_hi:[1,0,1] neg_lo:[0,0,1]
	v_pk_mul_f32 v[136:137], v[2:3], v[216:217] op_sel:[1,1] op_sel_hi:[0,1]
	v_pk_fma_f32 v[2:3], v[2:3], v[212:213], v[136:137] op_sel:[0,1,0] op_sel_hi:[1,1,1] neg_lo:[0,0,1]
	v_pk_mul_f32 v[8:9], v[8:9], s[36:37] op_sel_hi:[1,0]
	v_pk_mul_f32 v[10:11], v[10:11], s[36:37] op_sel_hi:[1,0]
	v_pk_mul_f32 v[0:1], v[0:1], s[36:37] op_sel_hi:[1,0]
	v_pk_mul_f32 v[2:3], v[2:3], s[36:37] op_sel_hi:[1,0]
	v_cvt_pk_bf16_f32 v144, v8, v9
	v_cvt_pk_bf16_f32 v145, v10, v11
	v_cvt_pk_bf16_f32 v146, v0, v1
	v_cvt_pk_bf16_f32 v147, v2, v3
	s_waitcnt lgkmcnt(0)
	global_store_dwordx4 v130, v[218:221], s[6:7] nt
	global_store_dwordx4 v130, v[222:225], s[6:7] offset:64 nt
	s_add_u32 s6, s6, s33
	s_addc_u32 s7, s7, 0
	ds_bpermute_b32 v226, v180, v140
	ds_bpermute_b32 v227, v180, v141
	ds_bpermute_b32 v228, v180, v142
	ds_bpermute_b32 v229, v180, v143
	ds_bpermute_b32 v230, v180, v144
	ds_bpermute_b32 v231, v180, v145
	ds_bpermute_b32 v232, v180, v146
	ds_bpermute_b32 v233, v180, v147
	s_waitcnt lgkmcnt(0)
	global_store_dwordx4 v130, v[226:229], s[6:7] nt
	global_store_dwordx4 v130, v[230:233], s[6:7] offset:64 nt
	s_branch .LBB0_638
.Lq3_B:
	global_load_dwordx4 v[148:151], v133, s[24:25]
	global_load_dwordx4 v[152:155], v133, s[24:25] offset:16
	global_load_dwordx4 v[156:159], v133, s[24:25] offset:128
	global_load_dwordx4 v[160:163], v133, s[24:25] offset:144
	v_mul_f32_e32 v134, v127, v127
	v_fmac_f32_e32 v134, v126, v126
	v_fmac_f32_e32 v134, v128, v128
	v_fmac_f32_e32 v134, v129, v129
	v_fmac_f32_e32 v134, v122, v122
	v_fmac_f32_e32 v134, v123, v123
	v_fmac_f32_e32 v134, v124, v124
	v_fmac_f32_e32 v134, v125, v125
	v_fmac_f32_e32 v134, v118, v118
	v_fmac_f32_e32 v134, v119, v119
	v_pk_mul_f32 v[136:137], v[120:121], v[120:121]
	v_pk_mul_f32 v[138:139], v[114:115], v[114:115]
	v_add_f32_e32 v134, v136, v134
	v_add_f32_e32 v134, v137, v134
	v_add_f32_e32 v134, v138, v134
	v_pk_mul_f32 v[136:137], v[116:117], v[116:117]
	v_add_f32_e32 v134, v139, v134
	v_add_f32_e32 v134, v136, v134
	v_add_f32_e32 v134, v137, v134
	ds_swizzle_b32 v135, v134 offset:swizzle(SWAP,16)
	s_waitcnt lgkmcnt(0)
	v_add_f32_e32 v134, v134, v135
	v_mov_b32_e32 v135, v134
	s_nop 1
	v_permlane32_swap_b32 v134, v135
	s_nop 1
	v_add_f32_e32 v134, v134, v135
	v_fmamk_f32 v134, v134, 0x3c800000, v242
	v_rsq_f32_e32 v134, v134
	s_waitcnt vmcnt(0)
	v_pk_mul_f32 v[136:137], v[134:135], v[148:149] op_sel_hi:[0,1]
	v_pk_mul_f32 v[126:127], v[126:127], v[136:137]
	v_pk_mul_f32 v[136:137], v[134:135], v[150:151] op_sel_hi:[0,1]
	v_pk_mul_f32 v[128:129], v[128:129], v[136:137]
	v_pk_mul_f32 v[136:137], v[134:135], v[152:153] op_sel_hi:[0,1]
	v_pk_mul_f32 v[122:123], v[122:123], v[136:137]
	v_pk_mul_f32 v[136:137], v[134:135], v[154:155] op_sel_hi:[0,1]
	v_pk_mul_f32 v[124:125], v[124:125], v[136:137]
	v_pk_mul_f32 v[136:137], v[134:135], v[156:157] op_sel_hi:[0,1]
	v_pk_mul_f32 v[118:119], v[118:119], v[136:137]
	v_pk_mul_f32 v[136:137], v[134:135], v[158:159] op_sel_hi:[0,1]
	v_pk_mul_f32 v[120:121], v[120:121], v[136:137]
	v_pk_mul_f32 v[136:137], v[134:135], v[160:161] op_sel_hi:[0,1]
	v_pk_mul_f32 v[114:115], v[114:115], v[136:137]
	v_pk_mul_f32 v[136:137], v[134:135], v[162:163] op_sel_hi:[0,1]
	v_pk_mul_f32 v[116:117], v[116:117], v[136:137]
	v_pk_mul_f32 v[126:127], v[126:127], s[36:37] op_sel_hi:[1,0]
	v_pk_mul_f32 v[128:129], v[128:129], s[36:37] op_sel_hi:[1,0]
	v_pk_mul_f32 v[122:123], v[122:123], s[36:37] op_sel_hi:[1,0]
	v_pk_mul_f32 v[124:125], v[124:125], s[36:37] op_sel_hi:[1,0]
	v_cvt_pk_bf16_f32 v140, v126, v127
	v_cvt_pk_bf16_f32 v141, v128, v129
	v_cvt_pk_bf16_f32 v142, v122, v123
	v_cvt_pk_bf16_f32 v143, v124, v125
	v_pk_mul_f32 v[118:119], v[118:119], s[36:37] op_sel_hi:[1,0]
	v_pk_mul_f32 v[120:121], v[120:121], s[36:37] op_sel_hi:[1,0]
	v_pk_mul_f32 v[114:115], v[114:115], s[36:37] op_sel_hi:[1,0]
	v_pk_mul_f32 v[116:117], v[116:117], s[36:37] op_sel_hi:[1,0]
	v_cvt_pk_bf16_f32 v144, v118, v119
	v_cvt_pk_bf16_f32 v145, v120, v121
	v_cvt_pk_bf16_f32 v146, v114, v115
	v_cvt_pk_bf16_f32 v147, v116, v117
	ds_bpermute_b32 v218, v180, v140
	ds_bpermute_b32 v219, v180, v141
	ds_bpermute_b32 v220, v180, v142
	ds_bpermute_b32 v221, v180, v143
	ds_bpermute_b32 v222, v180, v144
	ds_bpermute_b32 v223, v180, v145
	ds_bpermute_b32 v224, v180, v146
	ds_bpermute_b32 v225, v180, v147
	v_mul_f32_e32 v134, v109, v109
	v_fmac_f32_e32 v134, v108, v108
	v_fmac_f32_e32 v134, v110, v110
	v_fmac_f32_e32 v134, v111, v111
	v_fmac_f32_e32 v134, v104, v104
	v_fmac_f32_e32 v134, v105, v105
	v_fmac_f32_e32 v134, v106, v106
	v_fmac_f32_e32 v134, v107, v107
	v_fmac_f32_e32 v134, v100, v100
	v_fmac_f32_e32 v134, v101, v101
	v_pk_mul_f32 v[136:137], v[102:103], v[102:103]
	v_pk_mul_f32 v[138:139], v[96:97], v[96:97]
	v_add_f32_e32 v134, v136, v134
	v_add_f32_e32 v134, v137, v134
	v_add_f32_e32 v134, v138, v134
	v_pk_mul_f32 v[136:137], v[98:99], v[98:99]
	v_add_f32_e32 v134, v139, v134
	v_add_f32_e32 v134, v136, v134
	v_add_f32_e32 v134, v137, v134
	ds_swizzle_b32 v135, v134 offset:swizzle(SWAP,16)
	s_waitcnt lgkmcnt(0)
	v_add_f32_e32 v134, v134, v135
	v_mov_b32_e32 v135, v134
	s_nop 1
	v_permlane32_swap_b32 v134, v135
	s_nop 1
	v_add_f32_e32 v134, v134, v135
	v_fmamk_f32 v134, v134, 0x3c800000, v242
	v_rsq_f32_e32 v134, v134
	s_nop 0
	v_pk_mul_f32 v[136:137], v[134:135], v[148:149] op_sel_hi:[0,1]
	v_pk_mul_f32 v[108:109], v[108:109], v[136:137]
	v_pk_mul_f32 v[136:137], v[134:135], v[150:151] op_sel_hi:[0,1]
	v_pk_mul_f32 v[110:111], v[110:111], v[136:137]
	v_pk_mul_f32 v[136:137], v[134:135], v[152:153] op_sel_hi:[0,1]
	v_pk_mul_f32 v[104:105], v[104:105], v[136:137]
	v_pk_mul_f32 v[136:137], v[134:135], v[154:155] op_sel_hi:[0,1]
	v_pk_mul_f32 v[106:107], v[106:107], v[136:137]
	v_pk_mul_f32 v[136:137], v[134:135], v[156:157] op_sel_hi:[0,1]
	v_pk_mul_f32 v[100:101], v[100:101], v[136:137]
	v_pk_mul_f32 v[136:137], v[134:135], v[158:159] op_sel_hi:[0,1]
	v_pk_mul_f32 v[102:103], v[102:103], v[136:137]
	v_pk_mul_f32 v[136:137], v[134:135], v[160:161] op_sel_hi:[0,1]
	v_pk_mul_f32 v[96:97], v[96:97], v[136:137]
	v_pk_mul_f32 v[136:137], v[134:135], v[162:163] op_sel_hi:[0,1]
	v_pk_mul_f32 v[98:99], v[98:99], v[136:137]
	v_pk_mul_f32 v[108:109], v[108:109], s[36:37] op_sel_hi:[1,0]
	v_pk_mul_f32 v[110:111], v[110:111], s[36:37] op_sel_hi:[1,0]
	v_pk_mul_f32 v[104:105], v[104:105], s[36:37] op_sel_hi:[1,0]
	v_pk_mul_f32 v[106:107], v[106:107], s[36:37] op_sel_hi:[1,0]
	v_cvt_pk_bf16_f32 v140, v108, v109
	v_cvt_pk_bf16_f32 v141, v110, v111
	v_cvt_pk_bf16_f32 v142, v104, v105
	v_cvt_pk_bf16_f32 v143, v106, v107
	v_pk_mul_f32 v[100:101], v[100:101], s[36:37] op_sel_hi:[1,0]
	v_pk_mul_f32 v[102:103], v[102:103], s[36:37] op_sel_hi:[1,0]
	v_pk_mul_f32 v[96:97], v[96:97], s[36:37] op_sel_hi:[1,0]
	v_pk_mul_f32 v[98:99], v[98:99], s[36:37] op_sel_hi:[1,0]
	v_cvt_pk_bf16_f32 v144, v100, v101
	v_cvt_pk_bf16_f32 v145, v102, v103
	v_cvt_pk_bf16_f32 v146, v96, v97
	v_cvt_pk_bf16_f32 v147, v98, v99
	s_waitcnt lgkmcnt(0)
	global_store_dwordx4 v130, v[218:221], s[6:7] nt
	global_store_dwordx4 v130, v[222:225], s[6:7] offset:64 nt
	s_add_u32 s6, s6, s33
	s_addc_u32 s7, s7, 0
	ds_bpermute_b32 v226, v180, v140
	ds_bpermute_b32 v227, v180, v141
	ds_bpermute_b32 v228, v180, v142
	ds_bpermute_b32 v229, v180, v143
	ds_bpermute_b32 v230, v180, v144
	ds_bpermute_b32 v231, v180, v145
	ds_bpermute_b32 v232, v180, v146
	ds_bpermute_b32 v233, v180, v147
	v_mul_f32_e32 v134, v93, v93
	v_fmac_f32_e32 v134, v92, v92
	v_fmac_f32_e32 v134, v94, v94
	v_fmac_f32_e32 v134, v95, v95
	v_fmac_f32_e32 v134, v88, v88
	v_fmac_f32_e32 v134, v89, v89
	v_fmac_f32_e32 v134, v90, v90
	v_fmac_f32_e32 v134, v91, v91
	v_fmac_f32_e32 v134, v84, v84
	v_fmac_f32_e32 v134, v85, v85
	v_pk_mul_f32 v[136:137], v[86:87], v[86:87]
	v_pk_mul_f32 v[138:139], v[80:81], v[80:81]
	v_add_f32_e32 v134, v136, v134
	v_add_f32_e32 v134, v137, v134
	v_add_f32_e32 v134, v138, v134
	v_pk_mul_f32 v[136:137], v[82:83], v[82:83]
	v_add_f32_e32 v134, v139, v134
	v_add_f32_e32 v134, v136, v134
	v_add_f32_e32 v134, v137, v134
	ds_swizzle_b32 v135, v134 offset:swizzle(SWAP,16)
	s_waitcnt lgkmcnt(0)
	v_add_f32_e32 v134, v134, v135
	v_mov_b32_e32 v135, v134
	s_nop 1
	v_permlane32_swap_b32 v134, v135
	s_nop 1
	v_add_f32_e32 v134, v134, v135
	v_fmamk_f32 v134, v134, 0x3c800000, v242
	v_rsq_f32_e32 v134, v134
	s_nop 0
	v_pk_mul_f32 v[136:137], v[134:135], v[148:149] op_sel_hi:[0,1]
	v_pk_mul_f32 v[92:93], v[92:93], v[136:137]
	v_pk_mul_f32 v[136:137], v[134:135], v[150:151] op_sel_hi:[0,1]
	v_pk_mul_f32 v[94:95], v[94:95], v[136:137]
	v_pk_mul_f32 v[136:137], v[134:135], v[152:153] op_sel_hi:[0,1]
	v_pk_mul_f32 v[88:89], v[88:89], v[136:137]
	v_pk_mul_f32 v[136:137], v[134:135], v[154:155] op_sel_hi:[0,1]
	v_pk_mul_f32 v[90:91], v[90:91], v[136:137]
	v_pk_mul_f32 v[136:137], v[134:135], v[156:157] op_sel_hi:[0,1]
	v_pk_mul_f32 v[84:85], v[84:85], v[136:137]
	v_pk_mul_f32 v[136:137], v[134:135], v[158:159] op_sel_hi:[0,1]
	v_pk_mul_f32 v[86:87], v[86:87], v[136:137]
	v_pk_mul_f32 v[136:137], v[134:135], v[160:161] op_sel_hi:[0,1]
	v_pk_mul_f32 v[80:81], v[80:81], v[136:137]
	v_pk_mul_f32 v[136:137], v[134:135], v[162:163] op_sel_hi:[0,1]
	v_pk_mul_f32 v[82:83], v[82:83], v[136:137]
	v_pk_mul_f32 v[92:93], v[92:93], s[36:37] op_sel_hi:[1,0]
	v_pk_mul_f32 v[94:95], v[94:95], s[36:37] op_sel_hi:[1,0]
	v_pk_mul_f32 v[88:89], v[88:89], s[36:37] op_sel_hi:[1,0]
	v_pk_mul_f32 v[90:91], v[90:91], s[36:37] op_sel_hi:[1,0]
	v_cvt_pk_bf16_f32 v140, v92, v93
	v_cvt_pk_bf16_f32 v141, v94, v95
	v_cvt_pk_bf16_f32 v142, v88, v89
	v_cvt_pk_bf16_f32 v143, v90, v91
	v_pk_mul_f32 v[84:85], v[84:85], s[36:37] op_sel_hi:[1,0]
	v_pk_mul_f32 v[86:87], v[86:87], s[36:37] op_sel_hi:[1,0]
	v_pk_mul_f32 v[80:81], v[80:81], s[36:37] op_sel_hi:[1,0]
	v_pk_mul_f32 v[82:83], v[82:83], s[36:37] op_sel_hi:[1,0]
	v_cvt_pk_bf16_f32 v144, v84, v85
	v_cvt_pk_bf16_f32 v145, v86, v87
	v_cvt_pk_bf16_f32 v146, v80, v81
	v_cvt_pk_bf16_f32 v147, v82, v83
	s_waitcnt lgkmcnt(0)
	global_store_dwordx4 v130, v[226:229], s[6:7] nt
	global_store_dwordx4 v130, v[230:233], s[6:7] offset:64 nt
	s_add_u32 s6, s6, s33
	s_addc_u32 s7, s7, 0
	ds_bpermute_b32 v218, v180, v140
	ds_bpermute_b32 v219, v180, v141
	ds_bpermute_b32 v220, v180, v142
	ds_bpermute_b32 v221, v180, v143
	ds_bpermute_b32 v222, v180, v144
	ds_bpermute_b32 v223, v180, v145
	ds_bpermute_b32 v224, v180, v146
	ds_bpermute_b32 v225, v180, v147
	v_mul_f32_e32 v134, v77, v77
	v_fmac_f32_e32 v134, v76, v76
	v_fmac_f32_e32 v134, v78, v78
	v_fmac_f32_e32 v134, v79, v79
	v_fmac_f32_e32 v134, v72, v72
	v_fmac_f32_e32 v134, v73, v73
	v_fmac_f32_e32 v134, v74, v74
	v_fmac_f32_e32 v134, v75, v75
	v_fmac_f32_e32 v134, v68, v68
	v_fmac_f32_e32 v134, v69, v69
	v_pk_mul_f32 v[136:137], v[70:71], v[70:71]
	v_pk_mul_f32 v[138:139], v[64:65], v[64:65]
	v_add_f32_e32 v134, v136, v134
	v_add_f32_e32 v134, v137, v134
	v_add_f32_e32 v134, v138, v134
	v_pk_mul_f32 v[136:137], v[66:67], v[66:67]
	v_add_f32_e32 v134, v139, v134
	v_add_f32_e32 v134, v136, v134
	v_add_f32_e32 v134, v137, v134
	ds_swizzle_b32 v135, v134 offset:swizzle(SWAP,16)
	s_waitcnt lgkmcnt(0)
	v_add_f32_e32 v134, v134, v135
	v_mov_b32_e32 v135, v134
	s_nop 1
	v_permlane32_swap_b32 v134, v135
	s_nop 1
	v_add_f32_e32 v134, v134, v135
	v_fmamk_f32 v134, v134, 0x3c800000, v242
	v_rsq_f32_e32 v134, v134
	s_nop 0
	v_pk_mul_f32 v[136:137], v[134:135], v[148:149] op_sel_hi:[0,1]
	v_pk_mul_f32 v[76:77], v[76:77], v[136:137]
	v_pk_mul_f32 v[136:137], v[134:135], v[150:151] op_sel_hi:[0,1]
	v_pk_mul_f32 v[78:79], v[78:79], v[136:137]
	v_pk_mul_f32 v[136:137], v[134:135], v[152:153] op_sel_hi:[0,1]
	v_pk_mul_f32 v[72:73], v[72:73], v[136:137]
	v_pk_mul_f32 v[136:137], v[134:135], v[154:155] op_sel_hi:[0,1]
	v_pk_mul_f32 v[74:75], v[74:75], v[136:137]
	v_pk_mul_f32 v[136:137], v[134:135], v[156:157] op_sel_hi:[0,1]
	v_pk_mul_f32 v[68:69], v[68:69], v[136:137]
	v_pk_mul_f32 v[136:137], v[134:135], v[158:159] op_sel_hi:[0,1]
	v_pk_mul_f32 v[70:71], v[70:71], v[136:137]
	v_pk_mul_f32 v[136:137], v[134:135], v[160:161] op_sel_hi:[0,1]
	v_pk_mul_f32 v[64:65], v[64:65], v[136:137]
	v_pk_mul_f32 v[136:137], v[134:135], v[162:163] op_sel_hi:[0,1]
	v_pk_mul_f32 v[66:67], v[66:67], v[136:137]
	v_pk_mul_f32 v[76:77], v[76:77], s[36:37] op_sel_hi:[1,0]
	v_pk_mul_f32 v[78:79], v[78:79], s[36:37] op_sel_hi:[1,0]
	v_pk_mul_f32 v[72:73], v[72:73], s[36:37] op_sel_hi:[1,0]
	v_pk_mul_f32 v[74:75], v[74:75], s[36:37] op_sel_hi:[1,0]
	v_cvt_pk_bf16_f32 v140, v76, v77
	v_cvt_pk_bf16_f32 v141, v78, v79
	v_cvt_pk_bf16_f32 v142, v72, v73
	v_cvt_pk_bf16_f32 v143, v74, v75
	v_pk_mul_f32 v[68:69], v[68:69], s[36:37] op_sel_hi:[1,0]
	v_pk_mul_f32 v[70:71], v[70:71], s[36:37] op_sel_hi:[1,0]
	v_pk_mul_f32 v[64:65], v[64:65], s[36:37] op_sel_hi:[1,0]
	v_pk_mul_f32 v[66:67], v[66:67], s[36:37] op_sel_hi:[1,0]
	v_cvt_pk_bf16_f32 v144, v68, v69
	v_cvt_pk_bf16_f32 v145, v70, v71
	v_cvt_pk_bf16_f32 v146, v64, v65
	v_cvt_pk_bf16_f32 v147, v66, v67
	s_waitcnt lgkmcnt(0)
	global_store_dwordx4 v130, v[218:221], s[6:7] nt
	global_store_dwordx4 v130, v[222:225], s[6:7] offset:64 nt
	s_add_u32 s6, s6, s33
	s_addc_u32 s7, s7, 0
	ds_bpermute_b32 v226, v180, v140
	ds_bpermute_b32 v227, v180, v141
	ds_bpermute_b32 v228, v180, v142
	ds_bpermute_b32 v229, v180, v143
	ds_bpermute_b32 v230, v180, v144
	ds_bpermute_b32 v231, v180, v145
	ds_bpermute_b32 v232, v180, v146
	ds_bpermute_b32 v233, v180, v147
	v_mul_f32_e32 v134, v61, v61
	v_fmac_f32_e32 v134, v60, v60
	v_fmac_f32_e32 v134, v62, v62
	v_fmac_f32_e32 v134, v63, v63
	v_fmac_f32_e32 v134, v56, v56
	v_fmac_f32_e32 v134, v57, v57
	v_fmac_f32_e32 v134, v58, v58
	v_fmac_f32_e32 v134, v59, v59
	v_fmac_f32_e32 v134, v52, v52
	v_fmac_f32_e32 v134, v53, v53
	v_pk_mul_f32 v[136:137], v[54:55], v[54:55]
	v_pk_mul_f32 v[138:139], v[48:49], v[48:49]
	v_add_f32_e32 v134, v136, v134
	v_add_f32_e32 v134, v137, v134
	v_add_f32_e32 v134, v138, v134
	v_pk_mul_f32 v[136:137], v[50:51], v[50:51]
	v_add_f32_e32 v134, v139, v134
	v_add_f32_e32 v134, v136, v134
	v_add_f32_e32 v134, v137, v134
	ds_swizzle_b32 v135, v134 offset:swizzle(SWAP,16)
	s_waitcnt lgkmcnt(0)
	v_add_f32_e32 v134, v134, v135
	v_mov_b32_e32 v135, v134
	s_nop 1
	v_permlane32_swap_b32 v134, v135
	s_nop 1
	v_add_f32_e32 v134, v134, v135
	v_fmamk_f32 v134, v134, 0x3c800000, v242
	v_rsq_f32_e32 v134, v134
	s_nop 0
	v_pk_mul_f32 v[136:137], v[134:135], v[148:149] op_sel_hi:[0,1]
	v_pk_mul_f32 v[60:61], v[60:61], v[136:137]
	v_pk_mul_f32 v[136:137], v[134:135], v[150:151] op_sel_hi:[0,1]
	v_pk_mul_f32 v[62:63], v[62:63], v[136:137]
	v_pk_mul_f32 v[136:137], v[134:135], v[152:153] op_sel_hi:[0,1]
	v_pk_mul_f32 v[56:57], v[56:57], v[136:137]
	v_pk_mul_f32 v[136:137], v[134:135], v[154:155] op_sel_hi:[0,1]
	v_pk_mul_f32 v[58:59], v[58:59], v[136:137]
	v_pk_mul_f32 v[136:137], v[134:135], v[156:157] op_sel_hi:[0,1]
	v_pk_mul_f32 v[52:53], v[52:53], v[136:137]
	v_pk_mul_f32 v[136:137], v[134:135], v[158:159] op_sel_hi:[0,1]
	v_pk_mul_f32 v[54:55], v[54:55], v[136:137]
	v_pk_mul_f32 v[136:137], v[134:135], v[160:161] op_sel_hi:[0,1]
	v_pk_mul_f32 v[48:49], v[48:49], v[136:137]
	v_pk_mul_f32 v[136:137], v[134:135], v[162:163] op_sel_hi:[0,1]
	v_pk_mul_f32 v[50:51], v[50:51], v[136:137]
	v_pk_mul_f32 v[60:61], v[60:61], s[36:37] op_sel_hi:[1,0]
	v_pk_mul_f32 v[62:63], v[62:63], s[36:37] op_sel_hi:[1,0]
	v_pk_mul_f32 v[56:57], v[56:57], s[36:37] op_sel_hi:[1,0]
	v_pk_mul_f32 v[58:59], v[58:59], s[36:37] op_sel_hi:[1,0]
	v_cvt_pk_bf16_f32 v140, v60, v61
	v_cvt_pk_bf16_f32 v141, v62, v63
	v_cvt_pk_bf16_f32 v142, v56, v57
	v_cvt_pk_bf16_f32 v143, v58, v59
	v_pk_mul_f32 v[52:53], v[52:53], s[36:37] op_sel_hi:[1,0]
	v_pk_mul_f32 v[54:55], v[54:55], s[36:37] op_sel_hi:[1,0]
	v_pk_mul_f32 v[48:49], v[48:49], s[36:37] op_sel_hi:[1,0]
	v_pk_mul_f32 v[50:51], v[50:51], s[36:37] op_sel_hi:[1,0]
	v_cvt_pk_bf16_f32 v144, v52, v53
	v_cvt_pk_bf16_f32 v145, v54, v55
	v_cvt_pk_bf16_f32 v146, v48, v49
	v_cvt_pk_bf16_f32 v147, v50, v51
	s_waitcnt lgkmcnt(0)
	global_store_dwordx4 v130, v[226:229], s[6:7] nt
	global_store_dwordx4 v130, v[230:233], s[6:7] offset:64 nt
	s_add_u32 s6, s6, s34
	s_addc_u32 s7, s7, 0
	ds_bpermute_b32 v218, v180, v140
	ds_bpermute_b32 v219, v180, v141
	ds_bpermute_b32 v220, v180, v142
	ds_bpermute_b32 v221, v180, v143
	ds_bpermute_b32 v222, v180, v144
	ds_bpermute_b32 v223, v180, v145
	ds_bpermute_b32 v224, v180, v146
	ds_bpermute_b32 v225, v180, v147
	v_mul_f32_e32 v134, v45, v45
	v_fmac_f32_e32 v134, v44, v44
	v_fmac_f32_e32 v134, v46, v46
	v_fmac_f32_e32 v134, v47, v47
	v_fmac_f32_e32 v134, v40, v40
	v_fmac_f32_e32 v134, v41, v41
	v_fmac_f32_e32 v134, v42, v42
	v_fmac_f32_e32 v134, v43, v43
	v_fmac_f32_e32 v134, v36, v36
	v_fmac_f32_e32 v134, v37, v37
	v_pk_mul_f32 v[136:137], v[38:39], v[38:39]
	v_pk_mul_f32 v[138:139], v[32:33], v[32:33]
	v_add_f32_e32 v134, v136, v134
	v_add_f32_e32 v134, v137, v134
	v_add_f32_e32 v134, v138, v134
	v_pk_mul_f32 v[136:137], v[34:35], v[34:35]
	v_add_f32_e32 v134, v139, v134
	v_add_f32_e32 v134, v136, v134
	v_add_f32_e32 v134, v137, v134
	ds_swizzle_b32 v135, v134 offset:swizzle(SWAP,16)
	s_waitcnt lgkmcnt(0)
	v_add_f32_e32 v134, v134, v135
	v_mov_b32_e32 v135, v134
	s_nop 1
	v_permlane32_swap_b32 v134, v135
	s_nop 1
	v_add_f32_e32 v134, v134, v135
	v_fmamk_f32 v134, v134, 0x3c800000, v242
	v_rsq_f32_e32 v134, v134
	s_nop 0
	v_pk_mul_f32 v[136:137], v[134:135], v[148:149] op_sel_hi:[0,1]
	v_pk_mul_f32 v[44:45], v[44:45], v[136:137]
	v_pk_mul_f32 v[136:137], v[134:135], v[150:151] op_sel_hi:[0,1]
	v_pk_mul_f32 v[46:47], v[46:47], v[136:137]
	v_pk_mul_f32 v[136:137], v[134:135], v[152:153] op_sel_hi:[0,1]
	v_pk_mul_f32 v[40:41], v[40:41], v[136:137]
	v_pk_mul_f32 v[136:137], v[134:135], v[154:155] op_sel_hi:[0,1]
	v_pk_mul_f32 v[42:43], v[42:43], v[136:137]
	v_pk_mul_f32 v[136:137], v[134:135], v[156:157] op_sel_hi:[0,1]
	v_pk_mul_f32 v[36:37], v[36:37], v[136:137]
	v_pk_mul_f32 v[136:137], v[134:135], v[158:159] op_sel_hi:[0,1]
	v_pk_mul_f32 v[38:39], v[38:39], v[136:137]
	v_pk_mul_f32 v[136:137], v[134:135], v[160:161] op_sel_hi:[0,1]
	v_pk_mul_f32 v[32:33], v[32:33], v[136:137]
	v_pk_mul_f32 v[136:137], v[134:135], v[162:163] op_sel_hi:[0,1]
	v_pk_mul_f32 v[34:35], v[34:35], v[136:137]
	v_pk_mul_f32 v[44:45], v[44:45], s[36:37] op_sel_hi:[1,0]
	v_pk_mul_f32 v[46:47], v[46:47], s[36:37] op_sel_hi:[1,0]
	v_pk_mul_f32 v[40:41], v[40:41], s[36:37] op_sel_hi:[1,0]
	v_pk_mul_f32 v[42:43], v[42:43], s[36:37] op_sel_hi:[1,0]
	v_cvt_pk_bf16_f32 v140, v44, v45
	v_cvt_pk_bf16_f32 v141, v46, v47
	v_cvt_pk_bf16_f32 v142, v40, v41
	v_cvt_pk_bf16_f32 v143, v42, v43
	v_pk_mul_f32 v[36:37], v[36:37], s[36:37] op_sel_hi:[1,0]
	v_pk_mul_f32 v[38:39], v[38:39], s[36:37] op_sel_hi:[1,0]
	v_pk_mul_f32 v[32:33], v[32:33], s[36:37] op_sel_hi:[1,0]
	v_pk_mul_f32 v[34:35], v[34:35], s[36:37] op_sel_hi:[1,0]
	v_cvt_pk_bf16_f32 v144, v36, v37
	v_cvt_pk_bf16_f32 v145, v38, v39
	v_cvt_pk_bf16_f32 v146, v32, v33
	v_cvt_pk_bf16_f32 v147, v34, v35
	s_waitcnt lgkmcnt(0)
	global_store_dwordx4 v130, v[218:221], s[6:7] nt
	global_store_dwordx4 v130, v[222:225], s[6:7] offset:64 nt
	s_add_u32 s6, s6, s33
	s_addc_u32 s7, s7, 0
	ds_bpermute_b32 v226, v180, v140
	ds_bpermute_b32 v227, v180, v141
	ds_bpermute_b32 v228, v180, v142
	ds_bpermute_b32 v229, v180, v143
	ds_bpermute_b32 v230, v180, v144
	ds_bpermute_b32 v231, v180, v145
	ds_bpermute_b32 v232, v180, v146
	ds_bpermute_b32 v233, v180, v147
	v_mul_f32_e32 v134, v29, v29
	v_fmac_f32_e32 v134, v28, v28
	v_fmac_f32_e32 v134, v30, v30
	v_fmac_f32_e32 v134, v31, v31
	v_fmac_f32_e32 v134, v24, v24
	v_fmac_f32_e32 v134, v25, v25
	v_fmac_f32_e32 v134, v26, v26
	v_fmac_f32_e32 v134, v27, v27
	v_fmac_f32_e32 v134, v20, v20
	v_fmac_f32_e32 v134, v21, v21
	v_pk_mul_f32 v[136:137], v[22:23], v[22:23]
	v_pk_mul_f32 v[138:139], v[16:17], v[16:17]
	v_add_f32_e32 v134, v136, v134
	v_add_f32_e32 v134, v137, v134
	v_add_f32_e32 v134, v138, v134
	v_pk_mul_f32 v[136:137], v[18:19], v[18:19]
	v_add_f32_e32 v134, v139, v134
	v_add_f32_e32 v134, v136, v134
	v_add_f32_e32 v134, v137, v134
	ds_swizzle_b32 v135, v134 offset:swizzle(SWAP,16)
	s_waitcnt lgkmcnt(0)
	v_add_f32_e32 v134, v134, v135
	v_mov_b32_e32 v135, v134
	s_nop 1
	v_permlane32_swap_b32 v134, v135
	s_nop 1
	v_add_f32_e32 v134, v134, v135
	v_fmamk_f32 v134, v134, 0x3c800000, v242
	v_rsq_f32_e32 v134, v134
	s_nop 0
	v_pk_mul_f32 v[136:137], v[134:135], v[148:149] op_sel_hi:[0,1]
	v_pk_mul_f32 v[28:29], v[28:29], v[136:137]
	v_pk_mul_f32 v[136:137], v[134:135], v[150:151] op_sel_hi:[0,1]
	v_pk_mul_f32 v[30:31], v[30:31], v[136:137]
	v_pk_mul_f32 v[136:137], v[134:135], v[152:153] op_sel_hi:[0,1]
	v_pk_mul_f32 v[24:25], v[24:25], v[136:137]
	v_pk_mul_f32 v[136:137], v[134:135], v[154:155] op_sel_hi:[0,1]
	v_pk_mul_f32 v[26:27], v[26:27], v[136:137]
	v_pk_mul_f32 v[136:137], v[134:135], v[156:157] op_sel_hi:[0,1]
	v_pk_mul_f32 v[20:21], v[20:21], v[136:137]
	v_pk_mul_f32 v[136:137], v[134:135], v[158:159] op_sel_hi:[0,1]
	v_pk_mul_f32 v[22:23], v[22:23], v[136:137]
	v_pk_mul_f32 v[136:137], v[134:135], v[160:161] op_sel_hi:[0,1]
	v_pk_mul_f32 v[16:17], v[16:17], v[136:137]
	v_pk_mul_f32 v[136:137], v[134:135], v[162:163] op_sel_hi:[0,1]
	v_pk_mul_f32 v[18:19], v[18:19], v[136:137]
	v_pk_mul_f32 v[28:29], v[28:29], s[36:37] op_sel_hi:[1,0]
	v_pk_mul_f32 v[30:31], v[30:31], s[36:37] op_sel_hi:[1,0]
	v_pk_mul_f32 v[24:25], v[24:25], s[36:37] op_sel_hi:[1,0]
	v_pk_mul_f32 v[26:27], v[26:27], s[36:37] op_sel_hi:[1,0]
	v_cvt_pk_bf16_f32 v140, v28, v29
	v_cvt_pk_bf16_f32 v141, v30, v31
	v_cvt_pk_bf16_f32 v142, v24, v25
	v_cvt_pk_bf16_f32 v143, v26, v27
	v_pk_mul_f32 v[20:21], v[20:21], s[36:37] op_sel_hi:[1,0]
	v_pk_mul_f32 v[22:23], v[22:23], s[36:37] op_sel_hi:[1,0]
	v_pk_mul_f32 v[16:17], v[16:17], s[36:37] op_sel_hi:[1,0]
	v_pk_mul_f32 v[18:19], v[18:19], s[36:37] op_sel_hi:[1,0]
	v_cvt_pk_bf16_f32 v144, v20, v21
	v_cvt_pk_bf16_f32 v145, v22, v23
	v_cvt_pk_bf16_f32 v146, v16, v17
	v_cvt_pk_bf16_f32 v147, v18, v19
	s_waitcnt lgkmcnt(0)
	global_store_dwordx4 v130, v[226:229], s[6:7] nt
	global_store_dwordx4 v130, v[230:233], s[6:7] offset:64 nt
	s_add_u32 s6, s6, s33
	s_addc_u32 s7, s7, 0
	ds_bpermute_b32 v218, v180, v140
	ds_bpermute_b32 v219, v180, v141
	ds_bpermute_b32 v220, v180, v142
	ds_bpermute_b32 v221, v180, v143
	ds_bpermute_b32 v222, v180, v144
	ds_bpermute_b32 v223, v180, v145
	ds_bpermute_b32 v224, v180, v146
	ds_bpermute_b32 v225, v180, v147
	v_mul_f32_e32 v134, v13, v13
	v_fmac_f32_e32 v134, v12, v12
	v_fmac_f32_e32 v134, v14, v14
	v_fmac_f32_e32 v134, v15, v15
	v_fmac_f32_e32 v134, v4, v4
	v_fmac_f32_e32 v134, v5, v5
	v_fmac_f32_e32 v134, v6, v6
	v_fmac_f32_e32 v134, v7, v7
	v_fmac_f32_e32 v134, v8, v8
	v_fmac_f32_e32 v134, v9, v9
	v_pk_mul_f32 v[136:137], v[10:11], v[10:11]
	v_pk_mul_f32 v[138:139], v[0:1], v[0:1]
	v_add_f32_e32 v134, v136, v134
	v_add_f32_e32 v134, v137, v134
	v_add_f32_e32 v134, v138, v134
	v_pk_mul_f32 v[136:137], v[2:3], v[2:3]
	v_add_f32_e32 v134, v139, v134
	v_add_f32_e32 v134, v136, v134
	v_add_f32_e32 v134, v137, v134
	ds_swizzle_b32 v135, v134 offset:swizzle(SWAP,16)
	s_waitcnt lgkmcnt(0)
	v_add_f32_e32 v134, v134, v135
	v_mov_b32_e32 v135, v134
	s_nop 1
	v_permlane32_swap_b32 v134, v135
	s_nop 1
	v_add_f32_e32 v134, v134, v135
	v_fmamk_f32 v134, v134, 0x3c800000, v242
	v_rsq_f32_e32 v134, v134
	s_nop 0
	v_pk_mul_f32 v[136:137], v[134:135], v[148:149] op_sel_hi:[0,1]
	v_pk_mul_f32 v[12:13], v[12:13], v[136:137]
	v_pk_mul_f32 v[136:137], v[134:135], v[150:151] op_sel_hi:[0,1]
	v_pk_mul_f32 v[14:15], v[14:15], v[136:137]
	v_pk_mul_f32 v[136:137], v[134:135], v[152:153] op_sel_hi:[0,1]
	v_pk_mul_f32 v[4:5], v[4:5], v[136:137]
	v_pk_mul_f32 v[136:137], v[134:135], v[154:155] op_sel_hi:[0,1]
	v_pk_mul_f32 v[6:7], v[6:7], v[136:137]
	v_pk_mul_f32 v[136:137], v[134:135], v[156:157] op_sel_hi:[0,1]
	v_pk_mul_f32 v[8:9], v[8:9], v[136:137]
	v_pk_mul_f32 v[136:137], v[134:135], v[158:159] op_sel_hi:[0,1]
	v_pk_mul_f32 v[10:11], v[10:11], v[136:137]
	v_pk_mul_f32 v[136:137], v[134:135], v[160:161] op_sel_hi:[0,1]
	v_pk_mul_f32 v[0:1], v[0:1], v[136:137]
	v_pk_mul_f32 v[136:137], v[134:135], v[162:163] op_sel_hi:[0,1]
	v_pk_mul_f32 v[2:3], v[2:3], v[136:137]
	v_pk_mul_f32 v[12:13], v[12:13], s[36:37] op_sel_hi:[1,0]
	v_pk_mul_f32 v[14:15], v[14:15], s[36:37] op_sel_hi:[1,0]
	v_pk_mul_f32 v[4:5], v[4:5], s[36:37] op_sel_hi:[1,0]
	v_pk_mul_f32 v[6:7], v[6:7], s[36:37] op_sel_hi:[1,0]
	v_cvt_pk_bf16_f32 v140, v12, v13
	v_cvt_pk_bf16_f32 v141, v14, v15
	v_cvt_pk_bf16_f32 v142, v4, v5
	v_cvt_pk_bf16_f32 v143, v6, v7
	v_pk_mul_f32 v[8:9], v[8:9], s[36:37] op_sel_hi:[1,0]
	v_pk_mul_f32 v[10:11], v[10:11], s[36:37] op_sel_hi:[1,0]
	v_pk_mul_f32 v[0:1], v[0:1], s[36:37] op_sel_hi:[1,0]
	v_pk_mul_f32 v[2:3], v[2:3], s[36:37] op_sel_hi:[1,0]
	v_cvt_pk_bf16_f32 v144, v8, v9
	v_cvt_pk_bf16_f32 v145, v10, v11
	v_cvt_pk_bf16_f32 v146, v0, v1
	v_cvt_pk_bf16_f32 v147, v2, v3
	s_waitcnt lgkmcnt(0)
	global_store_dwordx4 v130, v[218:221], s[6:7] nt
	global_store_dwordx4 v130, v[222:225], s[6:7] offset:64 nt
	s_add_u32 s6, s6, s33
	s_addc_u32 s7, s7, 0
	ds_bpermute_b32 v226, v180, v140
	ds_bpermute_b32 v227, v180, v141
	ds_bpermute_b32 v228, v180, v142
	ds_bpermute_b32 v229, v180, v143
	ds_bpermute_b32 v230, v180, v144
	ds_bpermute_b32 v231, v180, v145
	ds_bpermute_b32 v232, v180, v146
	ds_bpermute_b32 v233, v180, v147
	s_waitcnt lgkmcnt(0)
	global_store_dwordx4 v130, v[226:229], s[6:7] nt
	global_store_dwordx4 v130, v[230:233], s[6:7] offset:64 nt
	s_branch .LBB0_638
.Lq3_C:
	global_load_dwordx4 v[164:167], v131, s[8:9]
	global_load_dwordx4 v[168:171], v132, s[8:9]
	global_load_dwordx4 v[172:175], v131, s[8:9] offset:64
	global_load_dwordx4 v[176:179], v132, s[8:9] offset:64
	s_add_u32 s8, s8, 0x800
	s_addc_u32 s9, s9, 0
	global_load_dwordx4 v[202:205], v131, s[8:9]
	global_load_dwordx4 v[206:209], v132, s[8:9]
	global_load_dwordx4 v[210:213], v131, s[8:9] offset:64
	global_load_dwordx4 v[214:217], v132, s[8:9] offset:64
	s_waitcnt vmcnt(4)
	v_pk_mul_f32 v[136:137], v[126:127], v[168:169] op_sel:[1,0] op_sel_hi:[0,0]
	v_pk_fma_f32 v[126:127], v[126:127], v[164:165], v[136:137] op_sel:[0,0,0] op_sel_hi:[1,0,1] neg_lo:[0,0,1]
	v_pk_mul_f32 v[136:137], v[128:129], v[168:169] op_sel:[1,1] op_sel_hi:[0,1]
	v_pk_fma_f32 v[128:129], v[128:129], v[164:165], v[136:137] op_sel:[0,1,0] op_sel_hi:[1,1,1] neg_lo:[0,0,1]
	v_pk_mul_f32 v[136:137], v[122:123], v[170:171] op_sel:[1,0] op_sel_hi:[0,0]
	v_pk_fma_f32 v[122:123], v[122:123], v[166:167], v[136:137] op_sel:[0,0,0] op_sel_hi:[1,0,1] neg_lo:[0,0,1]
	v_pk_mul_f32 v[136:137], v[124:125], v[170:171] op_sel:[1,1] op_sel_hi:[0,1]
	v_pk_fma_f32 v[124:125], v[124:125], v[166:167], v[136:137] op_sel:[0,1,0] op_sel_hi:[1,1,1] neg_lo:[0,0,1]
	v_pk_mul_f32 v[126:127], v[126:127], s[36:37] op_sel_hi:[1,0]
	v_pk_mul_f32 v[128:129], v[128:129], s[36:37] op_sel_hi:[1,0]
	v_pk_mul_f32 v[122:123], v[122:123], s[36:37] op_sel_hi:[1,0]
	v_pk_mul_f32 v[124:125], v[124:125], s[36:37] op_sel_hi:[1,0]
	v_cvt_pk_bf16_f32 v140, v126, v127
	v_cvt_pk_bf16_f32 v141, v128, v129
	v_cvt_pk_bf16_f32 v142, v122, v123
	v_cvt_pk_bf16_f32 v143, v124, v125
	v_pk_mul_f32 v[136:137], v[118:119], v[176:177] op_sel:[1,0] op_sel_hi:[0,0]
	v_pk_fma_f32 v[118:119], v[118:119], v[172:173], v[136:137] op_sel:[0,0,0] op_sel_hi:[1,0,1] neg_lo:[0,0,1]
	v_pk_mul_f32 v[136:137], v[120:121], v[176:177] op_sel:[1,1] op_sel_hi:[0,1]
	v_pk_fma_f32 v[120:121], v[120:121], v[172:173], v[136:137] op_sel:[0,1,0] op_sel_hi:[1,1,1] neg_lo:[0,0,1]
	v_pk_mul_f32 v[136:137], v[114:115], v[178:179] op_sel:[1,0] op_sel_hi:[0,0]
	v_pk_fma_f32 v[114:115], v[114:115], v[174:175], v[136:137] op_sel:[0,0,0] op_sel_hi:[1,0,1] neg_lo:[0,0,1]
	v_pk_mul_f32 v[136:137], v[116:117], v[178:179] op_sel:[1,1] op_sel_hi:[0,1]
	v_pk_fma_f32 v[116:117], v[116:117], v[174:175], v[136:137] op_sel:[0,1,0] op_sel_hi:[1,1,1] neg_lo:[0,0,1]
	v_pk_mul_f32 v[118:119], v[118:119], s[36:37] op_sel_hi:[1,0]
	v_pk_mul_f32 v[120:121], v[120:121], s[36:37] op_sel_hi:[1,0]
	v_pk_mul_f32 v[114:115], v[114:115], s[36:37] op_sel_hi:[1,0]
	v_pk_mul_f32 v[116:117], v[116:117], s[36:37] op_sel_hi:[1,0]
	v_cvt_pk_bf16_f32 v144, v118, v119
	v_cvt_pk_bf16_f32 v145, v120, v121
	v_cvt_pk_bf16_f32 v146, v114, v115
	v_cvt_pk_bf16_f32 v147, v116, v117
	ds_bpermute_b32 v218, v180, v140
	ds_bpermute_b32 v219, v180, v141
	ds_bpermute_b32 v220, v180, v142
	ds_bpermute_b32 v221, v180, v143
	ds_bpermute_b32 v222, v180, v144
	ds_bpermute_b32 v223, v180, v145
	ds_bpermute_b32 v224, v180, v146
	ds_bpermute_b32 v225, v180, v147
	s_add_u32 s8, s8, 0x800
	s_addc_u32 s9, s9, 0
	global_load_dwordx4 v[164:167], v131, s[8:9]
	global_load_dwordx4 v[168:171], v132, s[8:9]
	global_load_dwordx4 v[172:175], v131, s[8:9] offset:64
	global_load_dwordx4 v[176:179], v132, s[8:9] offset:64
	s_waitcnt vmcnt(4)
	v_pk_mul_f32 v[136:137], v[108:109], v[206:207] op_sel:[1,0] op_sel_hi:[0,0]
	v_pk_fma_f32 v[108:109], v[108:109], v[202:203], v[136:137] op_sel:[0,0,0] op_sel_hi:[1,0,1] neg_lo:[0,0,1]
	v_pk_mul_f32 v[136:137], v[110:111], v[206:207] op_sel:[1,1] op_sel_hi:[0,1]
	v_pk_fma_f32 v[110:111], v[110:111], v[202:203], v[136:137] op_sel:[0,1,0] op_sel_hi:[1,1,1] neg_lo:[0,0,1]
	v_pk_mul_f32 v[136:137], v[104:105], v[208:209] op_sel:[1,0] op_sel_hi:[0,0]
	v_pk_fma_f32 v[104:105], v[104:105], v[204:205], v[136:137] op_sel:[0,0,0] op_sel_hi:[1,0,1] neg_lo:[0,0,1]
	v_pk_mul_f32 v[136:137], v[106:107], v[208:209] op_sel:[1,1] op_sel_hi:[0,1]
	v_pk_fma_f32 v[106:107], v[106:107], v[204:205], v[136:137] op_sel:[0,1,0] op_sel_hi:[1,1,1] neg_lo:[0,0,1]
	v_pk_mul_f32 v[108:109], v[108:109], s[36:37] op_sel_hi:[1,0]
	v_pk_mul_f32 v[110:111], v[110:111], s[36:37] op_sel_hi:[1,0]
	v_pk_mul_f32 v[104:105], v[104:105], s[36:37] op_sel_hi:[1,0]
	v_pk_mul_f32 v[106:107], v[106:107], s[36:37] op_sel_hi:[1,0]
	v_cvt_pk_bf16_f32 v140, v108, v109
	v_cvt_pk_bf16_f32 v141, v110, v111
	v_cvt_pk_bf16_f32 v142, v104, v105
	v_cvt_pk_bf16_f32 v143, v106, v107
	v_pk_mul_f32 v[136:137], v[100:101], v[214:215] op_sel:[1,0] op_sel_hi:[0,0]
	v_pk_fma_f32 v[100:101], v[100:101], v[210:211], v[136:137] op_sel:[0,0,0] op_sel_hi:[1,0,1] neg_lo:[0,0,1]
	v_pk_mul_f32 v[136:137], v[102:103], v[214:215] op_sel:[1,1] op_sel_hi:[0,1]
	v_pk_fma_f32 v[102:103], v[102:103], v[210:211], v[136:137] op_sel:[0,1,0] op_sel_hi:[1,1,1] neg_lo:[0,0,1]
	v_pk_mul_f32 v[136:137], v[96:97], v[216:217] op_sel:[1,0] op_sel_hi:[0,0]
	v_pk_fma_f32 v[96:97], v[96:97], v[212:213], v[136:137] op_sel:[0,0,0] op_sel_hi:[1,0,1] neg_lo:[0,0,1]
	v_pk_mul_f32 v[136:137], v[98:99], v[216:217] op_sel:[1,1] op_sel_hi:[0,1]
	v_pk_fma_f32 v[98:99], v[98:99], v[212:213], v[136:137] op_sel:[0,1,0] op_sel_hi:[1,1,1] neg_lo:[0,0,1]
	v_pk_mul_f32 v[100:101], v[100:101], s[36:37] op_sel_hi:[1,0]
	v_pk_mul_f32 v[102:103], v[102:103], s[36:37] op_sel_hi:[1,0]
	v_pk_mul_f32 v[96:97], v[96:97], s[36:37] op_sel_hi:[1,0]
	v_pk_mul_f32 v[98:99], v[98:99], s[36:37] op_sel_hi:[1,0]
	v_cvt_pk_bf16_f32 v144, v100, v101
	v_cvt_pk_bf16_f32 v145, v102, v103
	v_cvt_pk_bf16_f32 v146, v96, v97
	v_cvt_pk_bf16_f32 v147, v98, v99
	s_waitcnt lgkmcnt(0)
	global_store_dwordx4 v130, v[218:221], s[6:7] nt
	global_store_dwordx4 v130, v[222:225], s[6:7] offset:64 nt
	s_add_u32 s6, s6, s33
	s_addc_u32 s7, s7, 0
	ds_bpermute_b32 v226, v180, v140
	ds_bpermute_b32 v227, v180, v141
	ds_bpermute_b32 v228, v180, v142
	ds_bpermute_b32 v229, v180, v143
	ds_bpermute_b32 v230, v180, v144
	ds_bpermute_b32 v231, v180, v145
	ds_bpermute_b32 v232, v180, v146
	ds_bpermute_b32 v233, v180, v147
	s_add_u32 s8, s8, 0x800
	s_addc_u32 s9, s9, 0
	global_load_dwordx4 v[202:205], v131, s[8:9]
	global_load_dwordx4 v[206:209], v132, s[8:9]
	global_load_dwordx4 v[210:213], v131, s[8:9] offset:64
	global_load_dwordx4 v[214:217], v132, s[8:9] offset:64
	s_waitcnt vmcnt(6)
	v_pk_mul_f32 v[136:137], v[92:93], v[168:169] op_sel:[1,0] op_sel_hi:[0,0]
	v_pk_fma_f32 v[92:93], v[92:93], v[164:165], v[136:137] op_sel:[0,0,0] op_sel_hi:[1,0,1] neg_lo:[0,0,1]
	v_pk_mul_f32 v[136:137], v[94:95], v[168:169] op_sel:[1,1] op_sel_hi:[0,1]
	v_pk_fma_f32 v[94:95], v[94:95], v[164:165], v[136:137] op_sel:[0,1,0] op_sel_hi:[1,1,1] neg_lo:[0,0,1]
	v_pk_mul_f32 v[136:137], v[88:89], v[170:171] op_sel:[1,0] op_sel_hi:[0,0]
	v_pk_fma_f32 v[88:89], v[88:89], v[166:167], v[136:137] op_sel:[0,0,0] op_sel_hi:[1,0,1] neg_lo:[0,0,1]
	v_pk_mul_f32 v[136:137], v[90:91], v[170:171] op_sel:[1,1] op_sel_hi:[0,1]
	v_pk_fma_f32 v[90:91], v[90:91], v[166:167], v[136:137] op_sel:[0,1,0] op_sel_hi:[1,1,1] neg_lo:[0,0,1]
	v_pk_mul_f32 v[92:93], v[92:93], s[36:37] op_sel_hi:[1,0]
	v_pk_mul_f32 v[94:95], v[94:95], s[36:37] op_sel_hi:[1,0]
	v_pk_mul_f32 v[88:89], v[88:89], s[36:37] op_sel_hi:[1,0]
	v_pk_mul_f32 v[90:91], v[90:91], s[36:37] op_sel_hi:[1,0]
	v_cvt_pk_bf16_f32 v140, v92, v93
	v_cvt_pk_bf16_f32 v141, v94, v95
	v_cvt_pk_bf16_f32 v142, v88, v89
	v_cvt_pk_bf16_f32 v143, v90, v91
	v_pk_mul_f32 v[136:137], v[84:85], v[176:177] op_sel:[1,0] op_sel_hi:[0,0]
	v_pk_fma_f32 v[84:85], v[84:85], v[172:173], v[136:137] op_sel:[0,0,0] op_sel_hi:[1,0,1] neg_lo:[0,0,1]
	v_pk_mul_f32 v[136:137], v[86:87], v[176:177] op_sel:[1,1] op_sel_hi:[0,1]
	v_pk_fma_f32 v[86:87], v[86:87], v[172:173], v[136:137] op_sel:[0,1,0] op_sel_hi:[1,1,1] neg_lo:[0,0,1]
	v_pk_mul_f32 v[136:137], v[80:81], v[178:179] op_sel:[1,0] op_sel_hi:[0,0]
	v_pk_fma_f32 v[80:81], v[80:81], v[174:175], v[136:137] op_sel:[0,0,0] op_sel_hi:[1,0,1] neg_lo:[0,0,1]
	v_pk_mul_f32 v[136:137], v[82:83], v[178:179] op_sel:[1,1] op_sel_hi:[0,1]
	v_pk_fma_f32 v[82:83], v[82:83], v[174:175], v[136:137] op_sel:[0,1,0] op_sel_hi:[1,1,1] neg_lo:[0,0,1]
	v_pk_mul_f32 v[84:85], v[84:85], s[36:37] op_sel_hi:[1,0]
	v_pk_mul_f32 v[86:87], v[86:87], s[36:37] op_sel_hi:[1,0]
	v_pk_mul_f32 v[80:81], v[80:81], s[36:37] op_sel_hi:[1,0]
	v_pk_mul_f32 v[82:83], v[82:83], s[36:37] op_sel_hi:[1,0]
	v_cvt_pk_bf16_f32 v144, v84, v85
	v_cvt_pk_bf16_f32 v145, v86, v87
	v_cvt_pk_bf16_f32 v146, v80, v81
	v_cvt_pk_bf16_f32 v147, v82, v83
	s_waitcnt lgkmcnt(0)
	global_store_dwordx4 v130, v[226:229], s[6:7] nt
	global_store_dwordx4 v130, v[230:233], s[6:7] offset:64 nt
	s_add_u32 s6, s6, s33
	s_addc_u32 s7, s7, 0
	ds_bpermute_b32 v218, v180, v140
	ds_bpermute_b32 v219, v180, v141
	ds_bpermute_b32 v220, v180, v142
	ds_bpermute_b32 v221, v180, v143
	ds_bpermute_b32 v222, v180, v144
	ds_bpermute_b32 v223, v180, v145
	ds_bpermute_b32 v224, v180, v146
	ds_bpermute_b32 v225, v180, v147
	s_add_u32 s8, s8, 0x2800
	s_addc_u32 s9, s9, 0
	global_load_dwordx4 v[164:167], v131, s[8:9]
	global_load_dwordx4 v[168:171], v132, s[8:9]
	global_load_dwordx4 v[172:175], v131, s[8:9] offset:64
	global_load_dwordx4 v[176:179], v132, s[8:9] offset:64
	s_waitcnt vmcnt(6)
	v_pk_mul_f32 v[136:137], v[76:77], v[206:207] op_sel:[1,0] op_sel_hi:[0,0]
	v_pk_fma_f32 v[76:77], v[76:77], v[202:203], v[136:137] op_sel:[0,0,0] op_sel_hi:[1,0,1] neg_lo:[0,0,1]
	v_pk_mul_f32 v[136:137], v[78:79], v[206:207] op_sel:[1,1] op_sel_hi:[0,1]
	v_pk_fma_f32 v[78:79], v[78:79], v[202:203], v[136:137] op_sel:[0,1,0] op_sel_hi:[1,1,1] neg_lo:[0,0,1]
	v_pk_mul_f32 v[136:137], v[72:73], v[208:209] op_sel:[1,0] op_sel_hi:[0,0]
	v_pk_fma_f32 v[72:73], v[72:73], v[204:205], v[136:137] op_sel:[0,0,0] op_sel_hi:[1,0,1] neg_lo:[0,0,1]
	v_pk_mul_f32 v[136:137], v[74:75], v[208:209] op_sel:[1,1] op_sel_hi:[0,1]
	v_pk_fma_f32 v[74:75], v[74:75], v[204:205], v[136:137] op_sel:[0,1,0] op_sel_hi:[1,1,1] neg_lo:[0,0,1]
	v_pk_mul_f32 v[76:77], v[76:77], s[36:37] op_sel_hi:[1,0]
	v_pk_mul_f32 v[78:79], v[78:79], s[36:37] op_sel_hi:[1,0]
	v_pk_mul_f32 v[72:73], v[72:73], s[36:37] op_sel_hi:[1,0]
	v_pk_mul_f32 v[74:75], v[74:75], s[36:37] op_sel_hi:[1,0]
	v_cvt_pk_bf16_f32 v140, v76, v77
	v_cvt_pk_bf16_f32 v141, v78, v79
	v_cvt_pk_bf16_f32 v142, v72, v73
	v_cvt_pk_bf16_f32 v143, v74, v75
	v_pk_mul_f32 v[136:137], v[68:69], v[214:215] op_sel:[1,0] op_sel_hi:[0,0]
	v_pk_fma_f32 v[68:69], v[68:69], v[210:211], v[136:137] op_sel:[0,0,0] op_sel_hi:[1,0,1] neg_lo:[0,0,1]
	v_pk_mul_f32 v[136:137], v[70:71], v[214:215] op_sel:[1,1] op_sel_hi:[0,1]
	v_pk_fma_f32 v[70:71], v[70:71], v[210:211], v[136:137] op_sel:[0,1,0] op_sel_hi:[1,1,1] neg_lo:[0,0,1]
	v_pk_mul_f32 v[136:137], v[64:65], v[216:217] op_sel:[1,0] op_sel_hi:[0,0]
	v_pk_fma_f32 v[64:65], v[64:65], v[212:213], v[136:137] op_sel:[0,0,0] op_sel_hi:[1,0,1] neg_lo:[0,0,1]
	v_pk_mul_f32 v[136:137], v[66:67], v[216:217] op_sel:[1,1] op_sel_hi:[0,1]
	v_pk_fma_f32 v[66:67], v[66:67], v[212:213], v[136:137] op_sel:[0,1,0] op_sel_hi:[1,1,1] neg_lo:[0,0,1]
	v_pk_mul_f32 v[68:69], v[68:69], s[36:37] op_sel_hi:[1,0]
	v_pk_mul_f32 v[70:71], v[70:71], s[36:37] op_sel_hi:[1,0]
	v_pk_mul_f32 v[64:65], v[64:65], s[36:37] op_sel_hi:[1,0]
	v_pk_mul_f32 v[66:67], v[66:67], s[36:37] op_sel_hi:[1,0]
	v_cvt_pk_bf16_f32 v144, v68, v69
	v_cvt_pk_bf16_f32 v145, v70, v71
	v_cvt_pk_bf16_f32 v146, v64, v65
	v_cvt_pk_bf16_f32 v147, v66, v67
	s_waitcnt lgkmcnt(0)
	global_store_dwordx4 v130, v[218:221], s[6:7] nt
	global_store_dwordx4 v130, v[222:225], s[6:7] offset:64 nt
	s_add_u32 s6, s6, s33
	s_addc_u32 s7, s7, 0
	ds_bpermute_b32 v226, v180, v140
	ds_bpermute_b32 v227, v180, v141
	ds_bpermute_b32 v228, v180, v142
	ds_bpermute_b32 v229, v180, v143
	ds_bpermute_b32 v230, v180, v144
	ds_bpermute_b32 v231, v180, v145
	ds_bpermute_b32 v232, v180, v146
	ds_bpermute_b32 v233, v180, v147
	s_add_u32 s8, s8, 0x800
	s_addc_u32 s9, s9, 0
	global_load_dwordx4 v[202:205], v131, s[8:9]
	global_load_dwordx4 v[206:209], v132, s[8:9]
	global_load_dwordx4 v[210:213], v131, s[8:9] offset:64
	global_load_dwordx4 v[214:217], v132, s[8:9] offset:64
	s_waitcnt vmcnt(6)
	v_pk_mul_f32 v[136:137], v[60:61], v[168:169] op_sel:[1,0] op_sel_hi:[0,0]
	v_pk_fma_f32 v[60:61], v[60:61], v[164:165], v[136:137] op_sel:[0,0,0] op_sel_hi:[1,0,1] neg_lo:[0,0,1]
	v_pk_mul_f32 v[136:137], v[62:63], v[168:169] op_sel:[1,1] op_sel_hi:[0,1]
	v_pk_fma_f32 v[62:63], v[62:63], v[164:165], v[136:137] op_sel:[0,1,0] op_sel_hi:[1,1,1] neg_lo:[0,0,1]
	v_pk_mul_f32 v[136:137], v[56:57], v[170:171] op_sel:[1,0] op_sel_hi:[0,0]
	v_pk_fma_f32 v[56:57], v[56:57], v[166:167], v[136:137] op_sel:[0,0,0] op_sel_hi:[1,0,1] neg_lo:[0,0,1]
	v_pk_mul_f32 v[136:137], v[58:59], v[170:171] op_sel:[1,1] op_sel_hi:[0,1]
	v_pk_fma_f32 v[58:59], v[58:59], v[166:167], v[136:137] op_sel:[0,1,0] op_sel_hi:[1,1,1] neg_lo:[0,0,1]
	v_pk_mul_f32 v[60:61], v[60:61], s[36:37] op_sel_hi:[1,0]
	v_pk_mul_f32 v[62:63], v[62:63], s[36:37] op_sel_hi:[1,0]
	v_pk_mul_f32 v[56:57], v[56:57], s[36:37] op_sel_hi:[1,0]
	v_pk_mul_f32 v[58:59], v[58:59], s[36:37] op_sel_hi:[1,0]
	v_cvt_pk_bf16_f32 v140, v60, v61
	v_cvt_pk_bf16_f32 v141, v62, v63
	v_cvt_pk_bf16_f32 v142, v56, v57
	v_cvt_pk_bf16_f32 v143, v58, v59
	v_pk_mul_f32 v[136:137], v[52:53], v[176:177] op_sel:[1,0] op_sel_hi:[0,0]
	v_pk_fma_f32 v[52:53], v[52:53], v[172:173], v[136:137] op_sel:[0,0,0] op_sel_hi:[1,0,1] neg_lo:[0,0,1]
	v_pk_mul_f32 v[136:137], v[54:55], v[176:177] op_sel:[1,1] op_sel_hi:[0,1]
	v_pk_fma_f32 v[54:55], v[54:55], v[172:173], v[136:137] op_sel:[0,1,0] op_sel_hi:[1,1,1] neg_lo:[0,0,1]
	v_pk_mul_f32 v[136:137], v[48:49], v[178:179] op_sel:[1,0] op_sel_hi:[0,0]
	v_pk_fma_f32 v[48:49], v[48:49], v[174:175], v[136:137] op_sel:[0,0,0] op_sel_hi:[1,0,1] neg_lo:[0,0,1]
	v_pk_mul_f32 v[136:137], v[50:51], v[178:179] op_sel:[1,1] op_sel_hi:[0,1]
	v_pk_fma_f32 v[50:51], v[50:51], v[174:175], v[136:137] op_sel:[0,1,0] op_sel_hi:[1,1,1] neg_lo:[0,0,1]
	v_pk_mul_f32 v[52:53], v[52:53], s[36:37] op_sel_hi:[1,0]
	v_pk_mul_f32 v[54:55], v[54:55], s[36:37] op_sel_hi:[1,0]
	v_pk_mul_f32 v[48:49], v[48:49], s[36:37] op_sel_hi:[1,0]
	v_pk_mul_f32 v[50:51], v[50:51], s[36:37] op_sel_hi:[1,0]
	v_cvt_pk_bf16_f32 v144, v52, v53
	v_cvt_pk_bf16_f32 v145, v54, v55
	v_cvt_pk_bf16_f32 v146, v48, v49
	v_cvt_pk_bf16_f32 v147, v50, v51
	s_waitcnt lgkmcnt(0)
	global_store_dwordx4 v130, v[226:229], s[6:7] nt
	global_store_dwordx4 v130, v[230:233], s[6:7] offset:64 nt
	s_add_u32 s6, s6, s34
	s_addc_u32 s7, s7, 0
	ds_bpermute_b32 v218, v180, v140
	ds_bpermute_b32 v219, v180, v141
	ds_bpermute_b32 v220, v180, v142
	ds_bpermute_b32 v221, v180, v143
	ds_bpermute_b32 v222, v180, v144
	ds_bpermute_b32 v223, v180, v145
	ds_bpermute_b32 v224, v180, v146
	ds_bpermute_b32 v225, v180, v147
	s_add_u32 s8, s8, 0x800
	s_addc_u32 s9, s9, 0
	global_load_dwordx4 v[164:167], v131, s[8:9]
	global_load_dwordx4 v[168:171], v132, s[8:9]
	global_load_dwordx4 v[172:175], v131, s[8:9] offset:64
	global_load_dwordx4 v[176:179], v132, s[8:9] offset:64
	s_waitcnt vmcnt(6)
	v_pk_mul_f32 v[136:137], v[44:45], v[206:207] op_sel:[1,0] op_sel_hi:[0,0]
	v_pk_fma_f32 v[44:45], v[44:45], v[202:203], v[136:137] op_sel:[0,0,0] op_sel_hi:[1,0,1] neg_lo:[0,0,1]
	v_pk_mul_f32 v[136:137], v[46:47], v[206:207] op_sel:[1,1] op_sel_hi:[0,1]
	v_pk_fma_f32 v[46:47], v[46:47], v[202:203], v[136:137] op_sel:[0,1,0] op_sel_hi:[1,1,1] neg_lo:[0,0,1]
	v_pk_mul_f32 v[136:137], v[40:41], v[208:209] op_sel:[1,0] op_sel_hi:[0,0]
	v_pk_fma_f32 v[40:41], v[40:41], v[204:205], v[136:137] op_sel:[0,0,0] op_sel_hi:[1,0,1] neg_lo:[0,0,1]
	v_pk_mul_f32 v[136:137], v[42:43], v[208:209] op_sel:[1,1] op_sel_hi:[0,1]
	v_pk_fma_f32 v[42:43], v[42:43], v[204:205], v[136:137] op_sel:[0,1,0] op_sel_hi:[1,1,1] neg_lo:[0,0,1]
	v_pk_mul_f32 v[44:45], v[44:45], s[36:37] op_sel_hi:[1,0]
	v_pk_mul_f32 v[46:47], v[46:47], s[36:37] op_sel_hi:[1,0]
	v_pk_mul_f32 v[40:41], v[40:41], s[36:37] op_sel_hi:[1,0]
	v_pk_mul_f32 v[42:43], v[42:43], s[36:37] op_sel_hi:[1,0]
	v_cvt_pk_bf16_f32 v140, v44, v45
	v_cvt_pk_bf16_f32 v141, v46, v47
	v_cvt_pk_bf16_f32 v142, v40, v41
	v_cvt_pk_bf16_f32 v143, v42, v43
	v_pk_mul_f32 v[136:137], v[36:37], v[214:215] op_sel:[1,0] op_sel_hi:[0,0]
	v_pk_fma_f32 v[36:37], v[36:37], v[210:211], v[136:137] op_sel:[0,0,0] op_sel_hi:[1,0,1] neg_lo:[0,0,1]
	v_pk_mul_f32 v[136:137], v[38:39], v[214:215] op_sel:[1,1] op_sel_hi:[0,1]
	v_pk_fma_f32 v[38:39], v[38:39], v[210:211], v[136:137] op_sel:[0,1,0] op_sel_hi:[1,1,1] neg_lo:[0,0,1]
	v_pk_mul_f32 v[136:137], v[32:33], v[216:217] op_sel:[1,0] op_sel_hi:[0,0]
	v_pk_fma_f32 v[32:33], v[32:33], v[212:213], v[136:137] op_sel:[0,0,0] op_sel_hi:[1,0,1] neg_lo:[0,0,1]
	v_pk_mul_f32 v[136:137], v[34:35], v[216:217] op_sel:[1,1] op_sel_hi:[0,1]
	v_pk_fma_f32 v[34:35], v[34:35], v[212:213], v[136:137] op_sel:[0,1,0] op_sel_hi:[1,1,1] neg_lo:[0,0,1]
	v_pk_mul_f32 v[36:37], v[36:37], s[36:37] op_sel_hi:[1,0]
	v_pk_mul_f32 v[38:39], v[38:39], s[36:37] op_sel_hi:[1,0]
	v_pk_mul_f32 v[32:33], v[32:33], s[36:37] op_sel_hi:[1,0]
	v_pk_mul_f32 v[34:35], v[34:35], s[36:37] op_sel_hi:[1,0]
	v_cvt_pk_bf16_f32 v144, v36, v37
	v_cvt_pk_bf16_f32 v145, v38, v39
	v_cvt_pk_bf16_f32 v146, v32, v33
	v_cvt_pk_bf16_f32 v147, v34, v35
	s_waitcnt lgkmcnt(0)
	global_store_dwordx4 v130, v[218:221], s[6:7] nt
	global_store_dwordx4 v130, v[222:225], s[6:7] offset:64 nt
	s_add_u32 s6, s6, s33
	s_addc_u32 s7, s7, 0
	ds_bpermute_b32 v226, v180, v140
	ds_bpermute_b32 v227, v180, v141
	ds_bpermute_b32 v228, v180, v142
	ds_bpermute_b32 v229, v180, v143
	ds_bpermute_b32 v230, v180, v144
	ds_bpermute_b32 v231, v180, v145
	ds_bpermute_b32 v232, v180, v146
	ds_bpermute_b32 v233, v180, v147
	s_add_u32 s8, s8, 0x800
	s_addc_u32 s9, s9, 0
	global_load_dwordx4 v[202:205], v131, s[8:9]
	global_load_dwordx4 v[206:209], v132, s[8:9]
	global_load_dwordx4 v[210:213], v131, s[8:9] offset:64
	global_load_dwordx4 v[214:217], v132, s[8:9] offset:64
	s_waitcnt vmcnt(6)
	v_pk_mul_f32 v[136:137], v[28:29], v[168:169] op_sel:[1,0] op_sel_hi:[0,0]
	v_pk_fma_f32 v[28:29], v[28:29], v[164:165], v[136:137] op_sel:[0,0,0] op_sel_hi:[1,0,1] neg_lo:[0,0,1]
	v_pk_mul_f32 v[136:137], v[30:31], v[168:169] op_sel:[1,1] op_sel_hi:[0,1]
	v_pk_fma_f32 v[30:31], v[30:31], v[164:165], v[136:137] op_sel:[0,1,0] op_sel_hi:[1,1,1] neg_lo:[0,0,1]
	v_pk_mul_f32 v[136:137], v[24:25], v[170:171] op_sel:[1,0] op_sel_hi:[0,0]
	v_pk_fma_f32 v[24:25], v[24:25], v[166:167], v[136:137] op_sel:[0,0,0] op_sel_hi:[1,0,1] neg_lo:[0,0,1]
	v_pk_mul_f32 v[136:137], v[26:27], v[170:171] op_sel:[1,1] op_sel_hi:[0,1]
	v_pk_fma_f32 v[26:27], v[26:27], v[166:167], v[136:137] op_sel:[0,1,0] op_sel_hi:[1,1,1] neg_lo:[0,0,1]
	v_pk_mul_f32 v[28:29], v[28:29], s[36:37] op_sel_hi:[1,0]
	v_pk_mul_f32 v[30:31], v[30:31], s[36:37] op_sel_hi:[1,0]
	v_pk_mul_f32 v[24:25], v[24:25], s[36:37] op_sel_hi:[1,0]
	v_pk_mul_f32 v[26:27], v[26:27], s[36:37] op_sel_hi:[1,0]
	v_cvt_pk_bf16_f32 v140, v28, v29
	v_cvt_pk_bf16_f32 v141, v30, v31
	v_cvt_pk_bf16_f32 v142, v24, v25
	v_cvt_pk_bf16_f32 v143, v26, v27
	v_pk_mul_f32 v[136:137], v[20:21], v[176:177] op_sel:[1,0] op_sel_hi:[0,0]
	v_pk_fma_f32 v[20:21], v[20:21], v[172:173], v[136:137] op_sel:[0,0,0] op_sel_hi:[1,0,1] neg_lo:[0,0,1]
	v_pk_mul_f32 v[136:137], v[22:23], v[176:177] op_sel:[1,1] op_sel_hi:[0,1]
	v_pk_fma_f32 v[22:23], v[22:23], v[172:173], v[136:137] op_sel:[0,1,0] op_sel_hi:[1,1,1] neg_lo:[0,0,1]
	v_pk_mul_f32 v[136:137], v[16:17], v[178:179] op_sel:[1,0] op_sel_hi:[0,0]
	v_pk_fma_f32 v[16:17], v[16:17], v[174:175], v[136:137] op_sel:[0,0,0] op_sel_hi:[1,0,1] neg_lo:[0,0,1]
	v_pk_mul_f32 v[136:137], v[18:19], v[178:179] op_sel:[1,1] op_sel_hi:[0,1]
	v_pk_fma_f32 v[18:19], v[18:19], v[174:175], v[136:137] op_sel:[0,1,0] op_sel_hi:[1,1,1] neg_lo:[0,0,1]
	v_pk_mul_f32 v[20:21], v[20:21], s[36:37] op_sel_hi:[1,0]
	v_pk_mul_f32 v[22:23], v[22:23], s[36:37] op_sel_hi:[1,0]
	v_pk_mul_f32 v[16:17], v[16:17], s[36:37] op_sel_hi:[1,0]
	v_pk_mul_f32 v[18:19], v[18:19], s[36:37] op_sel_hi:[1,0]
	v_cvt_pk_bf16_f32 v144, v20, v21
	v_cvt_pk_bf16_f32 v145, v22, v23
	v_cvt_pk_bf16_f32 v146, v16, v17
	v_cvt_pk_bf16_f32 v147, v18, v19
	s_waitcnt lgkmcnt(0)
	global_store_dwordx4 v130, v[226:229], s[6:7] nt
	global_store_dwordx4 v130, v[230:233], s[6:7] offset:64 nt
	s_add_u32 s6, s6, s33
	s_addc_u32 s7, s7, 0
	ds_bpermute_b32 v218, v180, v140
	ds_bpermute_b32 v219, v180, v141
	ds_bpermute_b32 v220, v180, v142
	ds_bpermute_b32 v221, v180, v143
	ds_bpermute_b32 v222, v180, v144
	ds_bpermute_b32 v223, v180, v145
	ds_bpermute_b32 v224, v180, v146
	ds_bpermute_b32 v225, v180, v147
	s_waitcnt vmcnt(2)
	v_pk_mul_f32 v[136:137], v[12:13], v[206:207] op_sel:[1,0] op_sel_hi:[0,0]
	v_pk_fma_f32 v[12:13], v[12:13], v[202:203], v[136:137] op_sel:[0,0,0] op_sel_hi:[1,0,1] neg_lo:[0,0,1]
	v_pk_mul_f32 v[136:137], v[14:15], v[206:207] op_sel:[1,1] op_sel_hi:[0,1]
	v_pk_fma_f32 v[14:15], v[14:15], v[202:203], v[136:137] op_sel:[0,1,0] op_sel_hi:[1,1,1] neg_lo:[0,0,1]
	v_pk_mul_f32 v[136:137], v[4:5], v[208:209] op_sel:[1,0] op_sel_hi:[0,0]
	v_pk_fma_f32 v[4:5], v[4:5], v[204:205], v[136:137] op_sel:[0,0,0] op_sel_hi:[1,0,1] neg_lo:[0,0,1]
	v_pk_mul_f32 v[136:137], v[6:7], v[208:209] op_sel:[1,1] op_sel_hi:[0,1]
	v_pk_fma_f32 v[6:7], v[6:7], v[204:205], v[136:137] op_sel:[0,1,0] op_sel_hi:[1,1,1] neg_lo:[0,0,1]
	v_pk_mul_f32 v[12:13], v[12:13], s[36:37] op_sel_hi:[1,0]
	v_pk_mul_f32 v[14:15], v[14:15], s[36:37] op_sel_hi:[1,0]
	v_pk_mul_f32 v[4:5], v[4:5], s[36:37] op_sel_hi:[1,0]
	v_pk_mul_f32 v[6:7], v[6:7], s[36:37] op_sel_hi:[1,0]
	v_cvt_pk_bf16_f32 v140, v12, v13
	v_cvt_pk_bf16_f32 v141, v14, v15
	v_cvt_pk_bf16_f32 v142, v4, v5
	v_cvt_pk_bf16_f32 v143, v6, v7
	v_pk_mul_f32 v[136:137], v[8:9], v[214:215] op_sel:[1,0] op_sel_hi:[0,0]
	v_pk_fma_f32 v[8:9], v[8:9], v[210:211], v[136:137] op_sel:[0,0,0] op_sel_hi:[1,0,1] neg_lo:[0,0,1]
	v_pk_mul_f32 v[136:137], v[10:11], v[214:215] op_sel:[1,1] op_sel_hi:[0,1]
	v_pk_fma_f32 v[10:11], v[10:11], v[210:211], v[136:137] op_sel:[0,1,0] op_sel_hi:[1,1,1] neg_lo:[0,0,1]
	v_pk_mul_f32 v[136:137], v[0:1], v[216:217] op_sel:[1,0] op_sel_hi:[0,0]
	v_pk_fma_f32 v[0:1], v[0:1], v[212:213], v[136:137] op_sel:[0,0,0] op_sel_hi:[1,0,1] neg_lo:[0,0,1]
	v_pk_mul_f32 v[136:137], v[2:3], v[216:217] op_sel:[1,1] op_sel_hi:[0,1]
	v_pk_fma_f32 v[2:3], v[2:3], v[212:213], v[136:137] op_sel:[0,1,0] op_sel_hi:[1,1,1] neg_lo:[0,0,1]
	v_pk_mul_f32 v[8:9], v[8:9], s[36:37] op_sel_hi:[1,0]
	v_pk_mul_f32 v[10:11], v[10:11], s[36:37] op_sel_hi:[1,0]
	v_pk_mul_f32 v[0:1], v[0:1], s[36:37] op_sel_hi:[1,0]
	v_pk_mul_f32 v[2:3], v[2:3], s[36:37] op_sel_hi:[1,0]
	v_cvt_pk_bf16_f32 v144, v8, v9
	v_cvt_pk_bf16_f32 v145, v10, v11
	v_cvt_pk_bf16_f32 v146, v0, v1
	v_cvt_pk_bf16_f32 v147, v2, v3
	s_waitcnt lgkmcnt(0)
	global_store_dwordx4 v130, v[218:221], s[6:7] nt
	global_store_dwordx4 v130, v[222:225], s[6:7] offset:64 nt
	s_add_u32 s6, s6, s33
	s_addc_u32 s7, s7, 0
	ds_bpermute_b32 v226, v180, v140
	ds_bpermute_b32 v227, v180, v141
	ds_bpermute_b32 v228, v180, v142
	ds_bpermute_b32 v229, v180, v143
	ds_bpermute_b32 v230, v180, v144
	ds_bpermute_b32 v231, v180, v145
	ds_bpermute_b32 v232, v180, v146
	ds_bpermute_b32 v233, v180, v147
	s_waitcnt lgkmcnt(0)
	global_store_dwordx4 v130, v[226:229], s[6:7] nt
	global_store_dwordx4 v130, v[230:233], s[6:7] offset:64 nt
	s_branch .LBB0_638
.Lq3_D:
	v_pk_mul_f32 v[126:127], v[126:127], s[36:37] op_sel_hi:[1,0]
	v_pk_mul_f32 v[128:129], v[128:129], s[36:37] op_sel_hi:[1,0]
	v_pk_mul_f32 v[122:123], v[122:123], s[36:37] op_sel_hi:[1,0]
	v_pk_mul_f32 v[124:125], v[124:125], s[36:37] op_sel_hi:[1,0]
	v_cvt_pk_bf16_f32 v140, v126, v127
	v_cvt_pk_bf16_f32 v141, v128, v129
	v_cvt_pk_bf16_f32 v142, v122, v123
	v_cvt_pk_bf16_f32 v143, v124, v125
	v_pk_mul_f32 v[118:119], v[118:119], s[36:37] op_sel_hi:[1,0]
	v_pk_mul_f32 v[120:121], v[120:121], s[36:37] op_sel_hi:[1,0]
	v_pk_mul_f32 v[114:115], v[114:115], s[36:37] op_sel_hi:[1,0]
	v_pk_mul_f32 v[116:117], v[116:117], s[36:37] op_sel_hi:[1,0]
	v_cvt_pk_bf16_f32 v144, v118, v119
	v_cvt_pk_bf16_f32 v145, v120, v121
	v_cvt_pk_bf16_f32 v146, v114, v115
	v_cvt_pk_bf16_f32 v147, v116, v117
	ds_bpermute_b32 v218, v180, v140
	ds_bpermute_b32 v219, v180, v141
	ds_bpermute_b32 v220, v180, v142
	ds_bpermute_b32 v221, v180, v143
	ds_bpermute_b32 v222, v180, v144
	ds_bpermute_b32 v223, v180, v145
	ds_bpermute_b32 v224, v180, v146
	ds_bpermute_b32 v225, v180, v147
	v_pk_mul_f32 v[108:109], v[108:109], s[36:37] op_sel_hi:[1,0]
	v_pk_mul_f32 v[110:111], v[110:111], s[36:37] op_sel_hi:[1,0]
	v_pk_mul_f32 v[104:105], v[104:105], s[36:37] op_sel_hi:[1,0]
	v_pk_mul_f32 v[106:107], v[106:107], s[36:37] op_sel_hi:[1,0]
	v_cvt_pk_bf16_f32 v140, v108, v109
	v_cvt_pk_bf16_f32 v141, v110, v111
	v_cvt_pk_bf16_f32 v142, v104, v105
	v_cvt_pk_bf16_f32 v143, v106, v107
	v_pk_mul_f32 v[100:101], v[100:101], s[36:37] op_sel_hi:[1,0]
	v_pk_mul_f32 v[102:103], v[102:103], s[36:37] op_sel_hi:[1,0]
	v_pk_mul_f32 v[96:97], v[96:97], s[36:37] op_sel_hi:[1,0]
	v_pk_mul_f32 v[98:99], v[98:99], s[36:37] op_sel_hi:[1,0]
	v_cvt_pk_bf16_f32 v144, v100, v101
	v_cvt_pk_bf16_f32 v145, v102, v103
	v_cvt_pk_bf16_f32 v146, v96, v97
	v_cvt_pk_bf16_f32 v147, v98, v99
	s_waitcnt lgkmcnt(0)
	global_store_dwordx4 v130, v[218:221], s[6:7] nt
	global_store_dwordx4 v130, v[222:225], s[6:7] offset:64 nt
	s_add_u32 s6, s6, s33
	s_addc_u32 s7, s7, 0
	ds_bpermute_b32 v226, v180, v140
	ds_bpermute_b32 v227, v180, v141
	ds_bpermute_b32 v228, v180, v142
	ds_bpermute_b32 v229, v180, v143
	ds_bpermute_b32 v230, v180, v144
	ds_bpermute_b32 v231, v180, v145
	ds_bpermute_b32 v232, v180, v146
	ds_bpermute_b32 v233, v180, v147
	v_pk_mul_f32 v[92:93], v[92:93], s[36:37] op_sel_hi:[1,0]
	v_pk_mul_f32 v[94:95], v[94:95], s[36:37] op_sel_hi:[1,0]
	v_pk_mul_f32 v[88:89], v[88:89], s[36:37] op_sel_hi:[1,0]
	v_pk_mul_f32 v[90:91], v[90:91], s[36:37] op_sel_hi:[1,0]
	v_cvt_pk_bf16_f32 v140, v92, v93
	v_cvt_pk_bf16_f32 v141, v94, v95
	v_cvt_pk_bf16_f32 v142, v88, v89
	v_cvt_pk_bf16_f32 v143, v90, v91
	v_pk_mul_f32 v[84:85], v[84:85], s[36:37] op_sel_hi:[1,0]
	v_pk_mul_f32 v[86:87], v[86:87], s[36:37] op_sel_hi:[1,0]
	v_pk_mul_f32 v[80:81], v[80:81], s[36:37] op_sel_hi:[1,0]
	v_pk_mul_f32 v[82:83], v[82:83], s[36:37] op_sel_hi:[1,0]
	v_cvt_pk_bf16_f32 v144, v84, v85
	v_cvt_pk_bf16_f32 v145, v86, v87
	v_cvt_pk_bf16_f32 v146, v80, v81
	v_cvt_pk_bf16_f32 v147, v82, v83
	s_waitcnt lgkmcnt(0)
	global_store_dwordx4 v130, v[226:229], s[6:7] nt
	global_store_dwordx4 v130, v[230:233], s[6:7] offset:64 nt
	s_add_u32 s6, s6, s33
	s_addc_u32 s7, s7, 0
	ds_bpermute_b32 v218, v180, v140
	ds_bpermute_b32 v219, v180, v141
	ds_bpermute_b32 v220, v180, v142
	ds_bpermute_b32 v221, v180, v143
	ds_bpermute_b32 v222, v180, v144
	ds_bpermute_b32 v223, v180, v145
	ds_bpermute_b32 v224, v180, v146
	ds_bpermute_b32 v225, v180, v147
	v_pk_mul_f32 v[76:77], v[76:77], s[36:37] op_sel_hi:[1,0]
	v_pk_mul_f32 v[78:79], v[78:79], s[36:37] op_sel_hi:[1,0]
	v_pk_mul_f32 v[72:73], v[72:73], s[36:37] op_sel_hi:[1,0]
	v_pk_mul_f32 v[74:75], v[74:75], s[36:37] op_sel_hi:[1,0]
	v_cvt_pk_bf16_f32 v140, v76, v77
	v_cvt_pk_bf16_f32 v141, v78, v79
	v_cvt_pk_bf16_f32 v142, v72, v73
	v_cvt_pk_bf16_f32 v143, v74, v75
	v_pk_mul_f32 v[68:69], v[68:69], s[36:37] op_sel_hi:[1,0]
	v_pk_mul_f32 v[70:71], v[70:71], s[36:37] op_sel_hi:[1,0]
	v_pk_mul_f32 v[64:65], v[64:65], s[36:37] op_sel_hi:[1,0]
	v_pk_mul_f32 v[66:67], v[66:67], s[36:37] op_sel_hi:[1,0]
	v_cvt_pk_bf16_f32 v144, v68, v69
	v_cvt_pk_bf16_f32 v145, v70, v71
	v_cvt_pk_bf16_f32 v146, v64, v65
	v_cvt_pk_bf16_f32 v147, v66, v67
	s_waitcnt lgkmcnt(0)
	global_store_dwordx4 v130, v[218:221], s[6:7] nt
	global_store_dwordx4 v130, v[222:225], s[6:7] offset:64 nt
	s_add_u32 s6, s6, s33
	s_addc_u32 s7, s7, 0
	ds_bpermute_b32 v226, v180, v140
	ds_bpermute_b32 v227, v180, v141
	ds_bpermute_b32 v228, v180, v142
	ds_bpermute_b32 v229, v180, v143
	ds_bpermute_b32 v230, v180, v144
	ds_bpermute_b32 v231, v180, v145
	ds_bpermute_b32 v232, v180, v146
	ds_bpermute_b32 v233, v180, v147
	v_pk_mul_f32 v[60:61], v[60:61], s[36:37] op_sel_hi:[1,0]
	v_pk_mul_f32 v[62:63], v[62:63], s[36:37] op_sel_hi:[1,0]
	v_pk_mul_f32 v[56:57], v[56:57], s[36:37] op_sel_hi:[1,0]
	v_pk_mul_f32 v[58:59], v[58:59], s[36:37] op_sel_hi:[1,0]
	v_cvt_pk_bf16_f32 v140, v60, v61
	v_cvt_pk_bf16_f32 v141, v62, v63
	v_cvt_pk_bf16_f32 v142, v56, v57
	v_cvt_pk_bf16_f32 v143, v58, v59
	v_pk_mul_f32 v[52:53], v[52:53], s[36:37] op_sel_hi:[1,0]
	v_pk_mul_f32 v[54:55], v[54:55], s[36:37] op_sel_hi:[1,0]
	v_pk_mul_f32 v[48:49], v[48:49], s[36:37] op_sel_hi:[1,0]
	v_pk_mul_f32 v[50:51], v[50:51], s[36:37] op_sel_hi:[1,0]
	v_cvt_pk_bf16_f32 v144, v52, v53
	v_cvt_pk_bf16_f32 v145, v54, v55
	v_cvt_pk_bf16_f32 v146, v48, v49
	v_cvt_pk_bf16_f32 v147, v50, v51
	s_waitcnt lgkmcnt(0)
	global_store_dwordx4 v130, v[226:229], s[6:7] nt
	global_store_dwordx4 v130, v[230:233], s[6:7] offset:64 nt
	s_add_u32 s6, s6, s34
	s_addc_u32 s7, s7, 0
	ds_bpermute_b32 v218, v180, v140
	ds_bpermute_b32 v219, v180, v141
	ds_bpermute_b32 v220, v180, v142
	ds_bpermute_b32 v221, v180, v143
	ds_bpermute_b32 v222, v180, v144
	ds_bpermute_b32 v223, v180, v145
	ds_bpermute_b32 v224, v180, v146
	ds_bpermute_b32 v225, v180, v147
	v_pk_mul_f32 v[44:45], v[44:45], s[36:37] op_sel_hi:[1,0]
	v_pk_mul_f32 v[46:47], v[46:47], s[36:37] op_sel_hi:[1,0]
	v_pk_mul_f32 v[40:41], v[40:41], s[36:37] op_sel_hi:[1,0]
	v_pk_mul_f32 v[42:43], v[42:43], s[36:37] op_sel_hi:[1,0]
	v_cvt_pk_bf16_f32 v140, v44, v45
	v_cvt_pk_bf16_f32 v141, v46, v47
	v_cvt_pk_bf16_f32 v142, v40, v41
	v_cvt_pk_bf16_f32 v143, v42, v43
	v_pk_mul_f32 v[36:37], v[36:37], s[36:37] op_sel_hi:[1,0]
	v_pk_mul_f32 v[38:39], v[38:39], s[36:37] op_sel_hi:[1,0]
	v_pk_mul_f32 v[32:33], v[32:33], s[36:37] op_sel_hi:[1,0]
	v_pk_mul_f32 v[34:35], v[34:35], s[36:37] op_sel_hi:[1,0]
	v_cvt_pk_bf16_f32 v144, v36, v37
	v_cvt_pk_bf16_f32 v145, v38, v39
	v_cvt_pk_bf16_f32 v146, v32, v33
	v_cvt_pk_bf16_f32 v147, v34, v35
	s_waitcnt lgkmcnt(0)
	global_store_dwordx4 v130, v[218:221], s[6:7] nt
	global_store_dwordx4 v130, v[222:225], s[6:7] offset:64 nt
	s_add_u32 s6, s6, s33
	s_addc_u32 s7, s7, 0
	ds_bpermute_b32 v226, v180, v140
	ds_bpermute_b32 v227, v180, v141
	ds_bpermute_b32 v228, v180, v142
	ds_bpermute_b32 v229, v180, v143
	ds_bpermute_b32 v230, v180, v144
	ds_bpermute_b32 v231, v180, v145
	ds_bpermute_b32 v232, v180, v146
	ds_bpermute_b32 v233, v180, v147
	v_pk_mul_f32 v[28:29], v[28:29], s[36:37] op_sel_hi:[1,0]
	v_pk_mul_f32 v[30:31], v[30:31], s[36:37] op_sel_hi:[1,0]
	v_pk_mul_f32 v[24:25], v[24:25], s[36:37] op_sel_hi:[1,0]
	v_pk_mul_f32 v[26:27], v[26:27], s[36:37] op_sel_hi:[1,0]
	v_cvt_pk_bf16_f32 v140, v28, v29
	v_cvt_pk_bf16_f32 v141, v30, v31
	v_cvt_pk_bf16_f32 v142, v24, v25
	v_cvt_pk_bf16_f32 v143, v26, v27
	v_pk_mul_f32 v[20:21], v[20:21], s[36:37] op_sel_hi:[1,0]
	v_pk_mul_f32 v[22:23], v[22:23], s[36:37] op_sel_hi:[1,0]
	v_pk_mul_f32 v[16:17], v[16:17], s[36:37] op_sel_hi:[1,0]
	v_pk_mul_f32 v[18:19], v[18:19], s[36:37] op_sel_hi:[1,0]
	v_cvt_pk_bf16_f32 v144, v20, v21
	v_cvt_pk_bf16_f32 v145, v22, v23
	v_cvt_pk_bf16_f32 v146, v16, v17
	v_cvt_pk_bf16_f32 v147, v18, v19
	s_waitcnt lgkmcnt(0)
	global_store_dwordx4 v130, v[226:229], s[6:7] nt
	global_store_dwordx4 v130, v[230:233], s[6:7] offset:64 nt
	s_add_u32 s6, s6, s33
	s_addc_u32 s7, s7, 0
	ds_bpermute_b32 v218, v180, v140
	ds_bpermute_b32 v219, v180, v141
	ds_bpermute_b32 v220, v180, v142
	ds_bpermute_b32 v221, v180, v143
	ds_bpermute_b32 v222, v180, v144
	ds_bpermute_b32 v223, v180, v145
	ds_bpermute_b32 v224, v180, v146
	ds_bpermute_b32 v225, v180, v147
	v_pk_mul_f32 v[12:13], v[12:13], s[36:37] op_sel_hi:[1,0]
	v_pk_mul_f32 v[14:15], v[14:15], s[36:37] op_sel_hi:[1,0]
	v_pk_mul_f32 v[4:5], v[4:5], s[36:37] op_sel_hi:[1,0]
	v_pk_mul_f32 v[6:7], v[6:7], s[36:37] op_sel_hi:[1,0]
	v_cvt_pk_bf16_f32 v140, v12, v13
	v_cvt_pk_bf16_f32 v141, v14, v15
	v_cvt_pk_bf16_f32 v142, v4, v5
	v_cvt_pk_bf16_f32 v143, v6, v7
	v_pk_mul_f32 v[8:9], v[8:9], s[36:37] op_sel_hi:[1,0]
	v_pk_mul_f32 v[10:11], v[10:11], s[36:37] op_sel_hi:[1,0]
	v_pk_mul_f32 v[0:1], v[0:1], s[36:37] op_sel_hi:[1,0]
	v_pk_mul_f32 v[2:3], v[2:3], s[36:37] op_sel_hi:[1,0]
	v_cvt_pk_bf16_f32 v144, v8, v9
	v_cvt_pk_bf16_f32 v145, v10, v11
	v_cvt_pk_bf16_f32 v146, v0, v1
	v_cvt_pk_bf16_f32 v147, v2, v3
	s_waitcnt lgkmcnt(0)
	global_store_dwordx4 v130, v[218:221], s[6:7] nt
	global_store_dwordx4 v130, v[222:225], s[6:7] offset:64 nt
	s_add_u32 s6, s6, s33
	s_addc_u32 s7, s7, 0
	ds_bpermute_b32 v226, v180, v140
	ds_bpermute_b32 v227, v180, v141
	ds_bpermute_b32 v228, v180, v142
	ds_bpermute_b32 v229, v180, v143
	ds_bpermute_b32 v230, v180, v144
	ds_bpermute_b32 v231, v180, v145
	ds_bpermute_b32 v232, v180, v146
	ds_bpermute_b32 v233, v180, v147
	s_waitcnt lgkmcnt(0)
	global_store_dwordx4 v130, v[226:229], s[6:7] nt
	global_store_dwordx4 v130, v[230:233], s[6:7] offset:64 nt
	s_branch .LBB0_638
